# A loop: negm copy removed, canonicalizing v_max removed; C-FIXREF loop: scalar add pairs packed (on top of A SGPR-base DMA)
# baseline (speedup 1.0000x reference)
.LBB0_541:
	v_lshl_add_u64 v[164:165], v[160:161], 0, v[172:173]
	s_add_i32 s10, s0, 0xf000
	v_lshl_add_u64 v[96:97], v[164:165], 0, s[12:13]
	s_mov_b32 m0, s10
	v_lshl_add_u64 v[166:167], v[158:159], 0, v[172:173]
	global_load_lds_dwordx4 v[96:97], off
	v_lshl_add_u64 v[96:97], v[166:167], 0, s[14:15]
	s_mov_b32 m0, s8
	s_nop 0
	global_load_lds_dwordx4 v[96:97], off
	ds_read_b128 v[96:99], v201 offset:20480
	ds_read_b128 v[144:147], v201 offset:24576
	ds_read_b128 v[100:103], v202 offset:20480
	ds_read_b128 v[168:171], v202 offset:24576
	v_exp_f32_e32 v180, v80
	v_exp_f32_e32 v181, v81
	v_exp_f32_e32 v182, v82
	v_exp_f32_e32 v183, v83
	s_waitcnt lgkmcnt(0)
	v_mfma_f32_32x32x16_bf16 v[112:127], v[96:99], v[132:135], v[48:63]
	ds_read_b128 v[80:83], v204 offset:20480
	ds_read_b128 v[174:177], v204 offset:24576
	v_exp_f32_e32 v84, v84
	v_exp_f32_e32 v85, v85
	v_exp_f32_e32 v86, v86
	v_exp_f32_e32 v87, v87
	v_mfma_f32_32x32x16_bf16 v[112:127], v[100:103], v[128:131], v[112:127]
	v_cvt_pk_bf16_f32 v180, v180, v181
	v_cvt_pk_bf16_f32 v181, v182, v183
	v_cvt_pk_bf16_f32 v182, v84, v85
	v_cvt_pk_bf16_f32 v183, v86, v87
	v_mfma_f32_32x32x16_bf16 v[96:111], v[144:147], v[132:135], v[48:63]
	ds_read_b128 v[84:87], v203 offset:20480
	ds_read_b128 v[144:147], v203 offset:24576
	s_waitcnt lgkmcnt(0)
	v_mfma_f32_32x32x16_bf16 v[112:127], v[80:83], v[140:143], v[112:127]
	v_exp_f32_e32 v80, v88
	v_exp_f32_e32 v81, v89
	v_exp_f32_e32 v82, v90
	v_exp_f32_e32 v83, v91
	v_mfma_f32_32x32x16_bf16 v[112:127], v[84:87], v[136:139], v[112:127]
	v_exp_f32_e32 v84, v92
	v_exp_f32_e32 v85, v93
	v_exp_f32_e32 v86, v94
	v_exp_f32_e32 v87, v95
	v_mfma_f32_32x32x16_bf16 v[96:111], v[168:171], v[128:131], v[96:111]
	v_cvt_pk_bf16_f32 v168, v80, v81
	v_cvt_pk_bf16_f32 v169, v82, v83
	v_cvt_pk_bf16_f32 v170, v84, v85
	v_cvt_pk_bf16_f32 v171, v86, v87
	ds_read_b128 v[80:83], v206 offset:8192
	ds_read_b128 v[84:87], v206 offset:12288
	v_mfma_f32_32x32x16_bf16 v[96:111], v[174:177], v[140:143], v[96:111]
	s_waitcnt lgkmcnt(0)
	v_mfma_f32_32x32x16_bf16 v[0:15], v[84:87], v[180:183], v[0:15]
	ds_read_b128 v[88:91], v205 offset:8192
	ds_read_b128 v[92:95], v205 offset:12288
	v_exp_f32_e32 v217, v64
	v_exp_f32_e32 v218, v65
	v_exp_f32_e32 v219, v66
	v_exp_f32_e32 v216, v67
	v_exp_f32_e32 v221, v68
	v_exp_f32_e32 v222, v69
	v_mfma_f32_32x32x16_bf16 v[16:31], v[80:83], v[180:183], v[16:31]
	v_exp_f32_e32 v223, v70
	v_exp_f32_e32 v220, v71
	v_cvt_pk_bf16_f32 v64, v217, v218
	v_cvt_pk_bf16_f32 v65, v219, v216
	v_cvt_pk_bf16_f32 v66, v221, v222
	v_cvt_pk_bf16_f32 v67, v223, v220
	s_waitcnt lgkmcnt(0)
	v_mfma_f32_32x32x16_bf16 v[0:15], v[92:95], v[168:171], v[0:15]
	ds_read_b128 v[68:71], v200 offset:8192
	ds_read_b128 v[174:177], v200 offset:12288
	v_exp_f32_e32 v225, v72
	v_exp_f32_e32 v226, v73
	v_exp_f32_e32 v227, v74
	v_exp_f32_e32 v224, v75
	v_exp_f32_e32 v229, v76
	v_exp_f32_e32 v230, v77
	v_mfma_f32_32x32x16_bf16 v[16:31], v[88:91], v[168:171], v[16:31]
	v_exp_f32_e32 v231, v78
	v_exp_f32_e32 v228, v79
	v_cvt_pk_bf16_f32 v72, v225, v226
	v_cvt_pk_bf16_f32 v73, v227, v224
	v_cvt_pk_bf16_f32 v74, v229, v230
	v_cvt_pk_bf16_f32 v75, v231, v228
	v_mfma_f32_32x32x16_bf16 v[96:111], v[144:147], v[136:139], v[96:111]
	s_waitcnt lgkmcnt(0)
	v_mfma_f32_32x32x16_bf16 v[16:31], v[68:71], v[64:67], v[16:31]
	ds_read_b128 v[76:79], v151 offset:8192
	ds_read_b128 v[184:187], v151 offset:12288
	s_waitcnt lgkmcnt(0)
	v_mfma_f32_32x32x16_bf16 v[16:31], v[76:79], v[72:75], v[16:31]
	s_waitcnt vmcnt(2)
	s_mov_b32 m0, s0
	s_waitcnt lgkmcnt(0)
	s_barrier
	v_lshl_add_u64 v[68:69], v[164:165], 0, s[16:17]
	global_load_lds_dwordx4 v[68:69], off
	v_lshl_add_u64 v[68:69], v[166:167], 0, s[18:19]
	s_mov_b32 m0, s1
	s_nop 0
	global_load_lds_dwordx4 v[68:69], off
	ds_read_b128 v[68:71], v201 offset:40960
	ds_read_b128 v[188:191], v201 offset:45056
	v_mfma_f32_32x32x16_bf16 v[0:15], v[174:177], v[64:67], v[0:15]
	v_mov_b64_e32 v[146:147], s[38:39]
	v_mov_b64_e32 v[144:145], s[36:37]
	ds_read_b128 v[64:67], v202 offset:40960
	ds_read_b128 v[174:177], v202 offset:45056
	v_exp_f32_e32 v192, v112
	v_exp_f32_e32 v193, v113
	v_exp_f32_e32 v194, v114
	v_exp_f32_e32 v195, v115
	s_waitcnt lgkmcnt(0)
	v_mfma_f32_32x32x16_bf16 v[80:95], v[68:71], v[132:135], v[48:63]
	v_mfma_f32_32x32x16_bf16 v[32:47], v[144:147], v[180:183], v[32:47]
	v_mfma_f32_32x32x16_bf16 v[0:15], v[184:187], v[72:75], v[0:15]
	v_mfma_f32_32x32x16_bf16 v[80:95], v[64:67], v[128:131], v[80:95]
	ds_read_b128 v[112:115], v204 offset:40960
	ds_read_b128 v[180:183], v204 offset:45056
	v_exp_f32_e32 v116, v116
	v_exp_f32_e32 v117, v117
	v_exp_f32_e32 v118, v118
	v_exp_f32_e32 v119, v119
	v_cvt_pk_bf16_f32 v192, v192, v193
	v_cvt_pk_bf16_f32 v193, v194, v195
	v_mfma_f32_32x32x16_bf16 v[64:79], v[188:191], v[132:135], v[48:63]
	v_cvt_pk_bf16_f32 v194, v116, v117
	v_cvt_pk_bf16_f32 v195, v118, v119
	s_waitcnt lgkmcnt(0)
	v_mfma_f32_32x32x16_bf16 v[80:95], v[112:115], v[140:143], v[80:95]
	ds_read_b128 v[112:115], v203 offset:40960
	ds_read_b128 v[116:119], v203 offset:45056
	v_exp_f32_e32 v120, v120
	v_exp_f32_e32 v121, v121
	v_exp_f32_e32 v122, v122
	v_exp_f32_e32 v123, v123
	v_mfma_f32_32x32x16_bf16 v[32:47], v[144:147], v[168:171], v[32:47]
	v_mfma_f32_32x32x16_bf16 v[64:79], v[174:177], v[128:131], v[64:79]
	v_cvt_pk_bf16_f32 v174, v120, v121
	v_cvt_pk_bf16_f32 v175, v122, v123
	s_waitcnt lgkmcnt(0)
	v_mfma_f32_32x32x16_bf16 v[80:95], v[112:115], v[136:139], v[80:95]
	v_exp_f32_e32 v112, v124
	v_exp_f32_e32 v113, v125
	v_exp_f32_e32 v114, v126
	v_exp_f32_e32 v115, v127
	v_cvt_pk_bf16_f32 v176, v112, v113
	v_cvt_pk_bf16_f32 v177, v114, v115
	v_mfma_f32_32x32x16_bf16 v[64:79], v[180:183], v[140:143], v[64:79]
	ds_read_b128 v[112:115], v206 offset:28672
	ds_read_b128 v[120:123], v206 offset:32768
	s_waitcnt lgkmcnt(0)
	v_mfma_f32_32x32x16_bf16 v[0:15], v[120:123], v[192:195], v[0:15]
	ds_read_b128 v[124:127], v205 offset:28672
	ds_read_b128 v[180:183], v205 offset:32768
	v_exp_f32_e32 v121, v96
	v_exp_f32_e32 v96, v97
	v_exp_f32_e32 v97, v98
	v_pk_add_f32 v[122:123], v[162:163], v[218:219]
	v_exp_f32_e32 v120, v99
	v_pk_add_f32 v[98:99], v[156:157], v[216:217]
	v_mfma_f32_32x32x16_bf16 v[16:31], v[112:115], v[192:195], v[16:31]
	v_pk_add_f32 v[122:123], v[222:223], v[122:123]
	v_pk_add_f32 v[98:99], v[220:221], v[98:99]
	v_exp_f32_e32 v163, v100
	v_exp_f32_e32 v184, v101
	v_exp_f32_e32 v185, v102
	v_exp_f32_e32 v162, v103
	v_pk_add_f32 v[122:123], v[226:227], v[122:123]
	v_pk_add_f32 v[98:99], v[224:225], v[98:99]
	v_pk_add_f32 v[122:123], v[230:231], v[122:123]
	v_pk_add_f32 v[98:99], v[228:229], v[98:99]
	v_pk_add_f32 v[168:169], v[122:123], v[96:97]
	v_pk_add_f32 v[156:157], v[98:99], v[120:121]
	v_cvt_pk_bf16_f32 v96, v121, v96
	v_cvt_pk_bf16_f32 v97, v97, v120
	v_cvt_pk_bf16_f32 v98, v163, v184
	v_cvt_pk_bf16_f32 v99, v185, v162
	s_waitcnt lgkmcnt(0)
	v_mfma_f32_32x32x16_bf16 v[0:15], v[180:183], v[174:177], v[0:15]
	ds_read_b128 v[100:103], v200 offset:28672
	ds_read_b128 v[180:183], v200 offset:32768
	v_exp_f32_e32 v171, v104
	v_exp_f32_e32 v188, v105
	v_exp_f32_e32 v189, v106
	v_exp_f32_e32 v170, v107
	v_exp_f32_e32 v187, v108
	v_exp_f32_e32 v190, v109
	v_mfma_f32_32x32x16_bf16 v[64:79], v[116:119], v[136:139], v[64:79]
	v_exp_f32_e32 v191, v110
	v_exp_f32_e32 v186, v111
	v_cvt_pk_bf16_f32 v104, v171, v188
	v_cvt_pk_bf16_f32 v105, v189, v170
	v_cvt_pk_bf16_f32 v106, v187, v190
	v_cvt_pk_bf16_f32 v107, v191, v186
	v_mfma_f32_32x32x16_bf16 v[16:31], v[124:127], v[174:177], v[16:31]
	s_waitcnt lgkmcnt(0)
	v_mfma_f32_32x32x16_bf16 v[16:31], v[100:103], v[96:99], v[16:31]
	ds_read_b128 v[108:111], v151 offset:28672
	ds_read_b128 v[218:221], v151 offset:32768
	s_waitcnt lgkmcnt(0)
	v_mfma_f32_32x32x16_bf16 v[16:31], v[108:111], v[104:107], v[16:31]
	s_waitcnt vmcnt(2)
	s_mov_b32 m0, s4
	s_waitcnt lgkmcnt(0)
	s_barrier
	v_lshl_add_u64 v[100:101], v[164:165], 0, s[34:35]
	global_load_lds_dwordx4 v[100:101], off
	v_lshl_add_u64 v[100:101], v[166:167], 0, s[42:43]
	s_mov_b32 m0, s5
	s_add_i32 s11, 0, 0x10000
	global_load_lds_dwordx4 v[100:101], off
	v_add_u32_e32 v215, s11, v207
	ds_read_b128 v[100:103], v201 offset:61440
	ds_read_b128 v[222:225], v215
	v_mfma_f32_32x32x16_bf16 v[0:15], v[180:183], v[96:99], v[0:15]
	v_add_u32_e32 v216, s11, v208
	ds_read_b128 v[96:99], v202 offset:61440
	ds_read_b128 v[180:183], v216
	v_exp_f32_e32 v226, v80
	v_exp_f32_e32 v227, v81
	v_exp_f32_e32 v228, v82
	v_exp_f32_e32 v229, v83
	v_mfma_f32_32x32x16_bf16 v[32:47], v[144:147], v[192:195], v[32:47]
	v_mfma_f32_32x32x16_bf16 v[0:15], v[218:221], v[104:107], v[0:15]
	s_waitcnt lgkmcnt(0)
	v_mfma_f32_32x32x16_bf16 v[112:127], v[100:103], v[132:135], v[48:63]
	ds_read_b128 v[80:83], v204 offset:61440
	v_add_u32_e32 v217, s11, v209
	ds_read_b128 v[192:195], v217
	v_exp_f32_e32 v84, v84
	v_exp_f32_e32 v85, v85
	v_exp_f32_e32 v86, v86
	v_exp_f32_e32 v87, v87
	v_cvt_pk_bf16_f32 v220, v226, v227
	v_mfma_f32_32x32x16_bf16 v[112:127], v[96:99], v[128:131], v[112:127]
	v_cvt_pk_bf16_f32 v221, v228, v229
	v_mfma_f32_32x32x16_bf16 v[96:111], v[222:225], v[132:135], v[48:63]
	v_cvt_pk_bf16_f32 v222, v84, v85
	v_cvt_pk_bf16_f32 v223, v86, v87
	v_mfma_f32_32x32x16_bf16 v[32:47], v[144:147], v[174:177], v[32:47]
	v_add_u32_e32 v218, s11, v210
	v_exp_f32_e32 v88, v88
	v_exp_f32_e32 v89, v89
	v_exp_f32_e32 v90, v90
	v_exp_f32_e32 v91, v91
	s_waitcnt lgkmcnt(0)
	v_mfma_f32_32x32x16_bf16 v[112:127], v[80:83], v[140:143], v[112:127]
	ds_read_b128 v[80:83], v203 offset:61440
	ds_read_b128 v[84:87], v218
	s_waitcnt lgkmcnt(0)
	v_mfma_f32_32x32x16_bf16 v[112:127], v[80:83], v[136:139], v[112:127]
	v_exp_f32_e32 v80, v92
	v_exp_f32_e32 v81, v93
	v_exp_f32_e32 v82, v94
	v_exp_f32_e32 v83, v95
	v_cvt_pk_bf16_f32 v174, v88, v89
	v_cvt_pk_bf16_f32 v175, v90, v91
	v_cvt_pk_bf16_f32 v176, v80, v81
	v_mfma_f32_32x32x16_bf16 v[96:111], v[180:183], v[128:131], v[96:111]
	v_cvt_pk_bf16_f32 v177, v82, v83
	ds_read_b128 v[80:83], v206 offset:49152
	ds_read_b128 v[88:91], v206 offset:53248
	v_mfma_f32_32x32x16_bf16 v[96:111], v[192:195], v[140:143], v[96:111]
	s_waitcnt lgkmcnt(0)
	v_mfma_f32_32x32x16_bf16 v[0:15], v[88:91], v[220:223], v[0:15]
	ds_read_b128 v[92:95], v205 offset:49152
	ds_read_b128 v[180:183], v205 offset:53248
	v_exp_f32_e32 v193, v64
	v_exp_f32_e32 v194, v65
	v_exp_f32_e32 v195, v66
	v_exp_f32_e32 v192, v67
	v_exp_f32_e32 v229, v68
	v_exp_f32_e32 v230, v69
	v_mfma_f32_32x32x16_bf16 v[16:31], v[80:83], v[220:223], v[16:31]
	v_exp_f32_e32 v231, v70
	v_exp_f32_e32 v228, v71
	v_cvt_pk_bf16_f32 v64, v193, v194
	v_cvt_pk_bf16_f32 v65, v195, v192
	v_cvt_pk_bf16_f32 v66, v229, v230
	v_cvt_pk_bf16_f32 v67, v231, v228
	s_waitcnt lgkmcnt(0)
	v_mfma_f32_32x32x16_bf16 v[0:15], v[180:183], v[174:177], v[0:15]
	ds_read_b128 v[68:71], v200 offset:49152
	ds_read_b128 v[180:183], v200 offset:53248
	v_exp_f32_e32 v233, v72
	v_exp_f32_e32 v234, v73
	v_exp_f32_e32 v235, v74
	v_exp_f32_e32 v232, v75
	v_exp_f32_e32 v237, v76
	v_exp_f32_e32 v238, v77
	v_mfma_f32_32x32x16_bf16 v[16:31], v[92:95], v[174:177], v[16:31]
	v_exp_f32_e32 v239, v78
	v_exp_f32_e32 v236, v79
	v_cvt_pk_bf16_f32 v72, v233, v234
	v_cvt_pk_bf16_f32 v73, v235, v232
	v_cvt_pk_bf16_f32 v74, v237, v238
	v_cvt_pk_bf16_f32 v75, v239, v236
	v_mfma_f32_32x32x16_bf16 v[96:111], v[84:87], v[136:139], v[96:111]
	s_waitcnt lgkmcnt(0)
	v_mfma_f32_32x32x16_bf16 v[16:31], v[68:71], v[64:67], v[16:31]
	ds_read_b128 v[76:79], v151 offset:49152
	ds_read_b128 v[224:227], v151 offset:53248
	s_waitcnt lgkmcnt(0)
	v_mfma_f32_32x32x16_bf16 v[16:31], v[76:79], v[72:75], v[16:31]
	s_waitcnt vmcnt(2)
	s_mov_b32 m0, s6
	s_waitcnt lgkmcnt(0)
	s_barrier
; template <int TYPE, bool FIXREF>
; DI void attn_dense_unit(const Params& p, int layer, int head, int qb, char* lds, float bref) {
;     ...
;   for (int t = 0; t < NT - 4; t += 4) {
;     STEP(sA0, sA1, sB0, sB1, t, true, true, R0, R1, R3);
;     STEP(sB0, sB1, sA0, sA1, t + 1, true, true, R1, R2, R0);
;     STEP(sA0, sA1, sB0, sB1, t + 2, true, true, R2, R3, R1);
;     STEP(sB0, sB1, sA0, sA1, t + 3, true, true, R3, R0, R2);
;   }
	v_lshl_add_u64 v[68:69], v[164:165], 0, s[44:45]
	global_load_lds_dwordx4 v[68:69], off
	v_lshl_add_u64 v[68:69], v[166:167], 0, s[46:47]
	s_mov_b32 m0, s7
	s_nop 0
	global_load_lds_dwordx4 v[68:69], off
	ds_read_b128 v[68:71], v201
	ds_read_b128 v[164:167], v201 offset:4096
	v_mfma_f32_32x32x16_bf16 v[0:15], v[180:183], v[64:67], v[0:15]
	ds_read_b128 v[64:67], v202
	ds_read_b128 v[180:183], v202 offset:4096
	s_waitcnt lgkmcnt(0)
	v_mfma_f32_32x32x16_bf16 v[80:95], v[68:71], v[132:135], v[48:63]
	v_exp_f32_e32 v68, v112
	v_exp_f32_e32 v69, v113
	v_exp_f32_e32 v70, v114
	v_exp_f32_e32 v71, v115
	v_mfma_f32_32x32x16_bf16 v[32:47], v[144:147], v[220:223], v[32:47]
	v_mfma_f32_32x32x16_bf16 v[0:15], v[224:227], v[72:75], v[0:15]
	v_mfma_f32_32x32x16_bf16 v[80:95], v[64:67], v[128:131], v[80:95]
	v_exp_f32_e32 v64, v116
	v_exp_f32_e32 v65, v117
	v_exp_f32_e32 v66, v118
	v_exp_f32_e32 v67, v119
	v_cvt_pk_bf16_f32 v116, v68, v69
	v_cvt_pk_bf16_f32 v117, v70, v71
	v_cvt_pk_bf16_f32 v118, v64, v65
	v_cvt_pk_bf16_f32 v119, v66, v67
	v_mfma_f32_32x32x16_bf16 v[64:79], v[164:167], v[132:135], v[48:63]
	ds_read_b128 v[112:115], v204
	ds_read_b128 v[220:223], v204 offset:4096
	s_waitcnt lgkmcnt(0)
	v_mfma_f32_32x32x16_bf16 v[80:95], v[112:115], v[140:143], v[80:95]
	ds_read_b128 v[112:115], v203
	ds_read_b128 v[224:227], v203 offset:4096
	v_exp_f32_e32 v120, v120
	v_exp_f32_e32 v121, v121
	v_exp_f32_e32 v122, v122
	v_exp_f32_e32 v123, v123
	v_mfma_f32_32x32x16_bf16 v[32:47], v[144:147], v[174:177], v[32:47]
	v_mfma_f32_32x32x16_bf16 v[64:79], v[180:183], v[128:131], v[64:79]
	v_add_u32_e32 v166, 0, v211
	v_add_u32_e32 v167, s11, v211
	s_waitcnt lgkmcnt(0)
	v_mfma_f32_32x32x16_bf16 v[80:95], v[112:115], v[136:139], v[80:95]
	v_exp_f32_e32 v114, v124
	v_exp_f32_e32 v115, v125
	v_exp_f32_e32 v124, v126
	v_exp_f32_e32 v125, v127
	v_cvt_pk_bf16_f32 v112, v120, v121
	v_cvt_pk_bf16_f32 v113, v122, v123
	v_cvt_pk_bf16_f32 v114, v114, v115
	v_mfma_f32_32x32x16_bf16 v[64:79], v[220:223], v[140:143], v[64:79]
	v_cvt_pk_bf16_f32 v115, v124, v125
	ds_read_b128 v[120:123], v166 offset:61440
	ds_read_b128 v[124:127], v167
	s_waitcnt lgkmcnt(0)
	v_mfma_f32_32x32x16_bf16 v[0:15], v[124:127], v[116:119], v[0:15]
	v_add_u32_e32 v164, 0, v212
	v_add_u32_e32 v165, s11, v212
	ds_read_b128 v[174:177], v164 offset:61440
	ds_read_b128 v[180:183], v165
	v_exp_f32_e32 v127, v96
	v_exp_f32_e32 v222, v97
	v_exp_f32_e32 v223, v98
	v_mfma_f32_32x32x16_bf16 v[16:31], v[120:123], v[116:119], v[16:31]
	v_exp_f32_e32 v126, v99
	v_exp_f32_e32 v241, v100
	v_exp_f32_e32 v242, v101
	v_exp_f32_e32 v243, v102
	v_exp_f32_e32 v240, v103
	v_cvt_pk_bf16_f32 v96, v127, v222
	v_cvt_pk_bf16_f32 v97, v223, v126
	v_cvt_pk_bf16_f32 v98, v241, v242
	v_cvt_pk_bf16_f32 v99, v243, v240
	v_mfma_f32_32x32x16_bf16 v[32:47], v[144:147], v[116:119], v[32:47]
	v_exp_f32_e32 v125, v104
	v_exp_f32_e32 v104, v105
	v_exp_f32_e32 v105, v106
	v_exp_f32_e32 v124, v107
	v_pk_add_f32 v[106:107], v[162:163], v[156:157]
	v_pk_add_f32 v[168:169], v[184:185], v[168:169]
	v_pk_add_f32 v[106:107], v[170:171], v[106:107]
	v_pk_add_f32 v[168:169], v[188:189], v[168:169]
	v_pk_add_f32 v[106:107], v[186:187], v[106:107]
	v_pk_add_f32 v[168:169], v[190:191], v[168:169]
	v_pk_add_f32 v[106:107], v[106:107], v[192:193]
	s_waitcnt lgkmcnt(0)
	v_mfma_f32_32x32x16_bf16 v[0:15], v[180:183], v[112:115], v[0:15]
	v_pk_add_f32 v[168:169], v[168:169], v[194:195]
	v_pk_add_f32 v[106:107], v[228:229], v[106:107]
	v_pk_add_f32 v[168:169], v[230:231], v[168:169]
	v_pk_add_f32 v[106:107], v[232:233], v[106:107]
	v_pk_add_f32 v[168:169], v[234:235], v[168:169]
	v_pk_add_f32 v[106:107], v[236:237], v[106:107]
	v_add_u32_e32 v219, 0, v213
	v_mfma_f32_32x32x16_bf16 v[64:79], v[224:227], v[136:139], v[64:79]
	v_add_u32_e32 v220, s11, v213
	v_pk_add_f32 v[168:169], v[238:239], v[168:169]
	v_pk_add_f32 v[106:107], v[106:107], v[126:127]
	v_exp_f32_e32 v127, v108
	v_exp_f32_e32 v108, v109
	v_exp_f32_e32 v109, v110
	v_exp_f32_e32 v126, v111
	v_mfma_f32_32x32x16_bf16 v[16:31], v[174:177], v[112:115], v[16:31]
	ds_read_b128 v[100:103], v219 offset:61440
	ds_read_b128 v[120:123], v220
	v_pk_add_f32 v[168:169], v[168:169], v[222:223]
	v_pk_add_f32 v[106:107], v[240:241], v[106:107]
	v_pk_add_f32 v[168:169], v[242:243], v[168:169]
	v_pk_add_f32 v[106:107], v[124:125], v[106:107]
	v_pk_add_f32 v[168:169], v[104:105], v[168:169]
	v_mfma_f32_32x32x16_bf16 v[32:47], v[144:147], v[112:115], v[32:47]
	v_pk_add_f32 v[162:163], v[108:109], v[168:169]
	v_pk_add_f32 v[156:157], v[126:127], v[106:107]
	v_cvt_pk_bf16_f32 v104, v125, v104
	v_cvt_pk_bf16_f32 v105, v105, v124
	v_cvt_pk_bf16_f32 v106, v127, v108
	v_cvt_pk_bf16_f32 v107, v109, v126
	s_waitcnt lgkmcnt(0)
	v_mfma_f32_32x32x16_bf16 v[16:31], v[100:103], v[96:99], v[16:31]
	v_add_u32_e32 v168, 0, v214
	v_add_u32_e32 v169, s11, v214
	ds_read_b128 v[100:103], v168 offset:61440
	ds_read_b128 v[108:111], v169
	v_mfma_f32_32x32x16_bf16 v[0:15], v[120:123], v[96:99], v[0:15]
	s_waitcnt lgkmcnt(0)
	v_mfma_f32_32x32x16_bf16 v[16:31], v[100:103], v[104:107], v[16:31]
	v_mfma_f32_32x32x16_bf16 v[0:15], v[108:111], v[104:107], v[0:15]
	s_waitcnt vmcnt(2)
	s_waitcnt lgkmcnt(0)
	s_barrier
	s_add_i32 s9, s9, 4
	v_lshl_add_u64 v[158:159], v[158:159], 0, s[64:65]
	s_cmpk_lt_u32 s9, 0xf8
	v_lshl_add_u64 v[160:161], v[160:161], 0, s[66:67]
	s_cbranch_scc1 .LBB0_541
; template <int TYPE, bool FIXREF>
; DI void attn_dense_unit(const Params& p, int layer, int head, int qb, char* lds, float bref) {
;     ...
;   STEP(sA0, sA1, sB0, sB1, NT - 4, true, true, R0, R1, R3);
;   STEP(sB0, sB1, sA0, sA1, NT - 3, true, false, R1, R2, R0);
;   STEP(sA0, sA1, sB0, sB1, NT - 2, true, false, R2, R3, R1);
	s_mov_b64 s[0:1], 0xef10000
	s_mov_b32 m0, s10
	v_lshl_add_u64 v[96:97], v[154:155], 0, s[0:1]
	s_mov_b64 s[0:1], 0x7f80
	global_load_lds_dwordx4 v[96:97], off
	v_lshl_add_u64 v[96:97], v[152:153], 0, s[0:1]
	s_mov_b32 m0, s8
	s_mov_b64 s[88:89], 0x17618300
	global_load_lds_dwordx4 v[96:97], off
	ds_read_b128 v[96:99], v201 offset:20480
	ds_read_b128 v[144:147], v201 offset:24576
	s_mov_b64 s[62:63], 0x33ba200
	ds_read_b128 v[100:103], v202 offset:20480
	ds_read_b128 v[152:155], v202 offset:24576
	v_exp_f32_e32 v170, v80
	v_exp_f32_e32 v171, v81
	v_exp_f32_e32 v172, v82
	v_exp_f32_e32 v175, v83
	s_waitcnt lgkmcnt(0)
	v_mfma_f32_32x32x16_bf16 v[112:127], v[96:99], v[132:135], v[48:63]
	ds_read_b128 v[80:83], v204 offset:20480
	ds_read_b128 v[158:161], v204 offset:24576
	v_exp_f32_e32 v84, v84
	v_exp_f32_e32 v85, v85
	v_exp_f32_e32 v86, v86
	v_exp_f32_e32 v87, v87
	v_mfma_f32_32x32x16_bf16 v[112:127], v[100:103], v[128:131], v[112:127]
	v_cvt_pk_bf16_f32 v174, v170, v171
	v_cvt_pk_bf16_f32 v175, v172, v175
	v_cvt_pk_bf16_f32 v176, v84, v85
	v_cvt_pk_bf16_f32 v177, v86, v87
	v_mfma_f32_32x32x16_bf16 v[96:111], v[144:147], v[132:135], v[48:63]
	ds_read_b128 v[84:87], v203 offset:20480
	ds_read_b128 v[144:147], v203 offset:24576
	s_waitcnt lgkmcnt(0)
	v_mfma_f32_32x32x16_bf16 v[112:127], v[80:83], v[140:143], v[112:127]
	v_exp_f32_e32 v80, v88
	v_exp_f32_e32 v81, v89
	v_exp_f32_e32 v82, v90
	v_exp_f32_e32 v83, v91
	v_mfma_f32_32x32x16_bf16 v[112:127], v[84:87], v[136:139], v[112:127]
	v_exp_f32_e32 v84, v92
	v_exp_f32_e32 v85, v93
	v_exp_f32_e32 v86, v94
	v_exp_f32_e32 v87, v95
	v_cvt_pk_bf16_f32 v180, v80, v81
	v_cvt_pk_bf16_f32 v181, v82, v83
	v_cvt_pk_bf16_f32 v182, v84, v85
	v_mfma_f32_32x32x16_bf16 v[96:111], v[152:155], v[128:131], v[96:111]
	v_cvt_pk_bf16_f32 v183, v86, v87
	ds_read_b128 v[80:83], v206 offset:8192
	ds_read_b128 v[84:87], v206 offset:12288
	v_mfma_f32_32x32x16_bf16 v[96:111], v[158:161], v[140:143], v[96:111]
	s_waitcnt lgkmcnt(0)
	v_mfma_f32_32x32x16_bf16 v[0:15], v[84:87], v[174:177], v[0:15]
	ds_read_b128 v[88:91], v205 offset:8192
	ds_read_b128 v[92:95], v205 offset:12288
	v_exp_f32_e32 v153, v64
	v_exp_f32_e32 v171, v65
	v_exp_f32_e32 v184, v66
	v_exp_f32_e32 v152, v67
	v_exp_f32_e32 v170, v68
	v_exp_f32_e32 v172, v69
	v_exp_f32_e32 v186, v70
	v_exp_f32_e32 v154, v71
	v_mfma_f32_32x32x16_bf16 v[16:31], v[80:83], v[174:177], v[16:31]
	v_cvt_pk_bf16_f32 v64, v153, v171
	v_cvt_pk_bf16_f32 v65, v184, v152
	v_cvt_pk_bf16_f32 v66, v170, v172
	v_cvt_pk_bf16_f32 v67, v186, v154
	s_waitcnt lgkmcnt(0)
	v_mfma_f32_32x32x16_bf16 v[0:15], v[92:95], v[180:183], v[0:15]
	ds_read_b128 v[68:71], v200 offset:8192
	ds_read_b128 v[190:193], v200 offset:12288
	v_exp_f32_e32 v185, v72
	v_exp_f32_e32 v187, v73
	v_exp_f32_e32 v189, v74
	v_exp_f32_e32 v158, v75
	v_exp_f32_e32 v155, v76
	v_exp_f32_e32 v188, v77
	v_exp_f32_e32 v194, v78
	v_exp_f32_e32 v160, v79
	v_mfma_f32_32x32x16_bf16 v[96:111], v[144:147], v[136:139], v[96:111]
	v_cvt_pk_bf16_f32 v72, v185, v187
	v_cvt_pk_bf16_f32 v73, v189, v158
	v_cvt_pk_bf16_f32 v74, v155, v188
	v_cvt_pk_bf16_f32 v75, v194, v160
	v_mfma_f32_32x32x16_bf16 v[16:31], v[88:91], v[180:183], v[16:31]
	ds_read_b128 v[76:79], v151 offset:8192
	ds_read_b128 v[208:211], v151 offset:12288
	s_waitcnt lgkmcnt(0)
	v_mfma_f32_32x32x16_bf16 v[16:31], v[68:71], v[64:67], v[16:31]
	v_mfma_f32_32x32x16_bf16 v[16:31], v[76:79], v[72:75], v[16:31]
	s_waitcnt vmcnt(2)
	s_waitcnt lgkmcnt(0)
	s_barrier
	ds_read_b128 v[68:71], v201 offset:40960
	ds_read_b128 v[222:225], v201 offset:45056
	v_mfma_f32_32x32x16_bf16 v[0:15], v[190:193], v[64:67], v[0:15]
	v_mov_b64_e32 v[146:147], s[38:39]
	v_mov_b64_e32 v[144:145], s[36:37]
	v_exp_f32_e32 v159, v112
	v_exp_f32_e32 v161, v113
	v_exp_f32_e32 v195, v114
	v_exp_f32_e32 v207, v115
	v_mfma_f32_32x32x16_bf16 v[0:15], v[208:211], v[72:75], v[0:15]
	v_mfma_f32_32x32x16_bf16 v[32:47], v[144:147], v[174:177], v[32:47]
	ds_read_b128 v[64:67], v202 offset:40960
	ds_read_b128 v[174:177], v202 offset:45056
	s_waitcnt lgkmcnt(0)
	v_mfma_f32_32x32x16_bf16 v[80:95], v[68:71], v[132:135], v[48:63]
	ds_read_b128 v[112:115], v204 offset:40960
	ds_read_b128 v[190:193], v204 offset:45056
	v_exp_f32_e32 v116, v116
	v_exp_f32_e32 v117, v117
	v_exp_f32_e32 v118, v118
	v_exp_f32_e32 v119, v119
	v_mfma_f32_32x32x16_bf16 v[80:95], v[64:67], v[128:131], v[80:95]
	v_cvt_pk_bf16_f32 v208, v159, v161
	v_cvt_pk_bf16_f32 v209, v195, v207
	v_cvt_pk_bf16_f32 v210, v116, v117
	v_cvt_pk_bf16_f32 v211, v118, v119
	v_mfma_f32_32x32x16_bf16 v[64:79], v[222:225], v[132:135], v[48:63]
	s_waitcnt lgkmcnt(0)
	v_mfma_f32_32x32x16_bf16 v[80:95], v[112:115], v[140:143], v[80:95]
	ds_read_b128 v[112:115], v203 offset:40960
	ds_read_b128 v[222:225], v203 offset:45056
	v_exp_f32_e32 v116, v120
	v_exp_f32_e32 v117, v121
	v_exp_f32_e32 v118, v122
	v_exp_f32_e32 v119, v123
	v_mfma_f32_32x32x16_bf16 v[32:47], v[144:147], v[180:183], v[32:47]
	s_waitcnt lgkmcnt(0)
	v_mfma_f32_32x32x16_bf16 v[80:95], v[112:115], v[136:139], v[80:95]
	v_exp_f32_e32 v114, v126
	v_exp_f32_e32 v115, v127
	v_exp_f32_e32 v112, v124
	v_exp_f32_e32 v113, v125
	v_cvt_pk_bf16_f32 v120, v116, v117
	v_cvt_pk_bf16_f32 v123, v114, v115
	ds_read_b128 v[114:117], v206 offset:28672
	ds_read_b128 v[124:127], v206 offset:32768
	v_mfma_f32_32x32x16_bf16 v[64:79], v[174:177], v[128:131], v[64:79]
	v_cvt_pk_bf16_f32 v121, v118, v119
	v_cvt_pk_bf16_f32 v122, v112, v113
	v_mfma_f32_32x32x16_bf16 v[64:79], v[190:193], v[140:143], v[64:79]
	s_waitcnt lgkmcnt(0)
; template <int TYPE, bool FIXREF>
; DI void attn_dense_unit(const Params& p, int layer, int head, int qb, char* lds, float bref) {
;     ...
;   STEP(sB0, sB1, sA0, sA1, NT - 3, true, false, R1, R2, R0);
;   STEP(sA0, sA1, sB0, sB1, NT - 2, true, false, R2, R3, R1);
;   STEP(sB0, sB1, sA0, sA1, NT - 1, false, false, R3, R0, R2);
	v_mfma_f32_32x32x16_bf16 v[0:15], v[124:127], v[208:211], v[0:15]
	ds_read_b128 v[174:177], v205 offset:28672
	ds_read_b128 v[180:183], v205 offset:32768
	v_exp_f32_e32 v159, v96
	v_exp_f32_e32 v195, v97
	v_exp_f32_e32 v207, v98
	v_exp_f32_e32 v112, v99
	v_exp_f32_e32 v161, v100
	v_exp_f32_e32 v221, v101
	v_mfma_f32_32x32x16_bf16 v[16:31], v[114:117], v[208:211], v[16:31]
	v_exp_f32_e32 v226, v102
	v_exp_f32_e32 v114, v103
	v_cvt_pk_bf16_f32 v124, v159, v195
	v_cvt_pk_bf16_f32 v125, v207, v112
	v_cvt_pk_bf16_f32 v126, v161, v221
	v_cvt_pk_bf16_f32 v127, v226, v114
	s_waitcnt lgkmcnt(0)
	v_mfma_f32_32x32x16_bf16 v[0:15], v[180:183], v[120:123], v[0:15]
	ds_read_b128 v[96:99], v200 offset:28672
	ds_read_b128 v[180:183], v200 offset:32768
	v_exp_f32_e32 v113, v104
	v_exp_f32_e32 v227, v105
	v_exp_f32_e32 v228, v106
	v_exp_f32_e32 v116, v107
	v_exp_f32_e32 v115, v108
	v_exp_f32_e32 v229, v109
	v_exp_f32_e32 v230, v110
	v_exp_f32_e32 v118, v111
	v_mfma_f32_32x32x16_bf16 v[64:79], v[222:225], v[136:139], v[64:79]
	v_cvt_pk_bf16_f32 v190, v113, v227
	v_cvt_pk_bf16_f32 v191, v228, v116
	v_cvt_pk_bf16_f32 v192, v115, v229
	v_cvt_pk_bf16_f32 v193, v230, v118
	v_mfma_f32_32x32x16_bf16 v[16:31], v[174:177], v[120:123], v[16:31]
	ds_read_b128 v[100:103], v151 offset:28672
	ds_read_b128 v[174:177], v151 offset:32768
	s_waitcnt lgkmcnt(0)
	v_mfma_f32_32x32x16_bf16 v[16:31], v[96:99], v[124:127], v[16:31]
	v_mfma_f32_32x32x16_bf16 v[16:31], v[100:103], v[190:193], v[16:31]
	s_waitcnt vmcnt(0)
	s_waitcnt lgkmcnt(0)
	s_barrier
	ds_read_b128 v[222:225], v201 offset:61440
	ds_read_b128 v[212:215], v215
	v_mfma_f32_32x32x16_bf16 v[0:15], v[180:183], v[124:127], v[0:15]
	ds_read_b128 v[124:127], v202 offset:61440
	ds_read_b128 v[180:183], v216
	v_exp_f32_e32 v117, v80
	v_exp_f32_e32 v119, v81
	v_exp_f32_e32 v201, v82
	v_exp_f32_e32 v202, v83
	v_mfma_f32_32x32x16_bf16 v[0:15], v[174:177], v[190:193], v[0:15]
	s_waitcnt lgkmcnt(0)
	v_mfma_f32_32x32x16_bf16 v[96:111], v[222:225], v[132:135], v[48:63]
	v_mfma_f32_32x32x16_bf16 v[32:47], v[144:147], v[208:211], v[32:47]
	ds_read_b128 v[80:83], v204 offset:61440
	ds_read_b128 v[174:177], v217
	v_mfma_f32_32x32x16_bf16 v[96:111], v[124:127], v[128:131], v[96:111]
	v_exp_f32_e32 v124, v84
	v_exp_f32_e32 v125, v85
	v_exp_f32_e32 v126, v86
	v_exp_f32_e32 v87, v87
	v_cvt_pk_bf16_f32 v84, v117, v119
	v_cvt_pk_bf16_f32 v85, v201, v202
	v_cvt_pk_bf16_f32 v86, v124, v125
	v_cvt_pk_bf16_f32 v87, v126, v87
	v_mfma_f32_32x32x16_bf16 v[48:63], v[212:215], v[132:135], v[48:63]
	s_waitcnt lgkmcnt(0)
	v_mfma_f32_32x32x16_bf16 v[96:111], v[80:83], v[140:143], v[96:111]
	ds_read_b128 v[80:83], v203 offset:61440
	ds_read_b128 v[124:127], v218
	v_exp_f32_e32 v88, v88
	v_exp_f32_e32 v89, v89
	v_exp_f32_e32 v90, v90
	v_exp_f32_e32 v91, v91
	v_mfma_f32_32x32x16_bf16 v[32:47], v[144:147], v[120:123], v[32:47]
	s_waitcnt lgkmcnt(0)
	v_mfma_f32_32x32x16_bf16 v[96:111], v[80:83], v[136:139], v[96:111]
	v_exp_f32_e32 v82, v92
	v_exp_f32_e32 v83, v93
	v_exp_f32_e32 v92, v94
	v_exp_f32_e32 v93, v95
	v_cvt_pk_bf16_f32 v80, v88, v89
	v_cvt_pk_bf16_f32 v81, v90, v91
	v_cvt_pk_bf16_f32 v82, v82, v83
	v_mfma_f32_32x32x16_bf16 v[48:63], v[180:183], v[128:131], v[48:63]
	v_cvt_pk_bf16_f32 v83, v92, v93
	ds_read_b128 v[88:91], v206 offset:49152
	ds_read_b128 v[92:95], v206 offset:53248
	v_mfma_f32_32x32x16_bf16 v[48:63], v[174:177], v[140:143], v[48:63]
	s_waitcnt lgkmcnt(0)
	v_mfma_f32_32x32x16_bf16 v[0:15], v[92:95], v[84:87], v[0:15]
	ds_read_b128 v[120:123], v205 offset:49152
	ds_read_b128 v[128:131], v205 offset:53248
	v_exp_f32_e32 v117, v64
	v_exp_f32_e32 v132, v65
	v_exp_f32_e32 v133, v66
	v_exp_f32_e32 v64, v67
	v_exp_f32_e32 v119, v68
	v_exp_f32_e32 v134, v69
	v_exp_f32_e32 v135, v70
	v_exp_f32_e32 v66, v71
	v_mfma_f32_32x32x16_bf16 v[16:31], v[88:91], v[84:87], v[16:31]
	v_cvt_pk_bf16_f32 v88, v117, v132
	v_cvt_pk_bf16_f32 v89, v133, v64
	v_cvt_pk_bf16_f32 v90, v119, v134
	v_cvt_pk_bf16_f32 v91, v135, v66
	s_waitcnt lgkmcnt(0)
	v_mfma_f32_32x32x16_bf16 v[0:15], v[128:131], v[80:83], v[0:15]
	ds_read_b128 v[92:95], v200 offset:49152
	ds_read_b128 v[128:131], v200 offset:53248
	v_exp_f32_e32 v65, v72
	v_exp_f32_e32 v140, v73
	v_exp_f32_e32 v141, v74
	v_exp_f32_e32 v68, v75
	v_exp_f32_e32 v67, v76
	v_exp_f32_e32 v70, v79
	v_mfma_f32_32x32x16_bf16 v[48:63], v[124:127], v[136:139], v[48:63]
	v_exp_f32_e32 v124, v77
	v_exp_f32_e32 v125, v78
	v_cvt_pk_bf16_f32 v72, v65, v140
	v_cvt_pk_bf16_f32 v73, v141, v68
	v_cvt_pk_bf16_f32 v74, v67, v124
	v_cvt_pk_bf16_f32 v75, v125, v70
	v_mfma_f32_32x32x16_bf16 v[16:31], v[120:123], v[80:83], v[16:31]
	ds_read_b128 v[76:79], v151 offset:49152
	ds_read_b128 v[120:123], v151 offset:53248
	s_waitcnt lgkmcnt(0)
	v_mfma_f32_32x32x16_bf16 v[16:31], v[92:95], v[88:91], v[16:31]
	v_mfma_f32_32x32x16_bf16 v[16:31], v[76:79], v[72:75], v[16:31]
	s_waitcnt vmcnt(0)
	s_waitcnt lgkmcnt(0)
	s_barrier
; template <int TYPE, bool FIXREF>
; DI void attn_dense_unit(const Params& p, int layer, int head, int qb, char* lds, float bref) {
;     ...
;   STEP(sB0, sB1, sA0, sA1, NT - 1, false, false, R3, R0, R2);
;   lsum += ls0 + ls1 + ls2;
;   const float l = (NONES > 0 ? la[0] : 0.f) + lsum + __shfl_xor(lsum, 32);
	v_mfma_f32_32x32x16_bf16 v[0:15], v[128:131], v[88:91], v[0:15]
	v_exp_f32_e32 v69, v96
	v_exp_f32_e32 v71, v97
	v_exp_f32_e32 v77, v98
	v_exp_f32_e32 v78, v99
	v_mfma_f32_32x32x16_bf16 v[32:47], v[144:147], v[84:87], v[32:47]
	v_exp_f32_e32 v79, v100
	v_exp_f32_e32 v84, v101
	v_exp_f32_e32 v85, v102
	v_exp_f32_e32 v86, v103
	v_mfma_f32_32x32x16_bf16 v[32:47], v[144:147], v[80:83], v[32:47]
	v_cvt_pk_bf16_f32 v76, v69, v71
	v_cvt_pk_bf16_f32 v77, v77, v78
	v_cvt_pk_bf16_f32 v78, v79, v84
	v_cvt_pk_bf16_f32 v79, v85, v86
	v_exp_f32_e32 v69, v104
	v_exp_f32_e32 v71, v105
	v_exp_f32_e32 v80, v106
	v_exp_f32_e32 v81, v107
	v_exp_f32_e32 v82, v108
	v_exp_f32_e32 v83, v109
	v_exp_f32_e32 v84, v110
	v_exp_f32_e32 v85, v111
	v_mfma_f32_32x32x16_bf16 v[0:15], v[120:123], v[72:75], v[0:15]
	v_cvt_pk_bf16_f32 v73, v80, v81
	v_cvt_pk_bf16_f32 v74, v82, v83
	v_cvt_pk_bf16_f32 v75, v84, v85
	ds_read_b128 v[80:83], v166 offset:61440
	ds_read_b128 v[84:87], v167
	v_cvt_pk_bf16_f32 v72, v69, v71
	s_waitcnt lgkmcnt(0)
	v_mfma_f32_32x32x16_bf16 v[0:15], v[84:87], v[76:79], v[0:15]
	ds_read_b128 v[84:87], v164 offset:61440
	ds_read_b128 v[88:91], v165
	v_mfma_f32_32x32x16_bf16 v[16:31], v[80:83], v[76:79], v[16:31]
	v_exp_f32_e32 v69, v48
	v_add_f32_e32 v48, v163, v184
	v_add_f32_e32 v48, v186, v48
	v_add_f32_e32 v48, v189, v48
	v_add_f32_e32 v48, v194, v48
	v_add_f32_e32 v48, v48, v207
	v_add_f32_e32 v48, v226, v48
	v_add_f32_e32 v48, v228, v48
	v_add_f32_e32 v48, v230, v48
	s_waitcnt lgkmcnt(0)
	v_mfma_f32_32x32x16_bf16 v[0:15], v[88:91], v[72:75], v[0:15]
	v_exp_f32_e32 v88, v59
	v_exp_f32_e32 v59, v50
	v_add_f32_e32 v48, v48, v133
	v_exp_f32_e32 v71, v52
	v_exp_f32_e32 v52, v53
	v_exp_f32_e32 v53, v54
	v_add_f32_e32 v48, v135, v48
	v_mfma_f32_32x32x16_bf16 v[16:31], v[84:87], v[72:75], v[16:31]
	v_exp_f32_e32 v85, v56
	v_exp_f32_e32 v56, v58
	v_add_f32_e32 v48, v141, v48
	v_exp_f32_e32 v58, v62
	v_add_f32_e32 v48, v125, v48
	v_add_f32_e32 v48, v48, v59
	v_add_f32_e32 v48, v53, v48
	v_add_f32_e32 v48, v56, v48
	v_add_f32_e32 v91, v58, v48
	v_add_f32_e32 v48, v162, v171
	v_add_f32_e32 v48, v172, v48
	v_add_f32_e32 v48, v187, v48
	v_add_f32_e32 v48, v188, v48
	v_add_f32_e32 v48, v48, v195
	v_add_f32_e32 v48, v221, v48
	v_add_f32_e32 v48, v227, v48
	v_add_f32_e32 v48, v229, v48
	v_exp_f32_e32 v86, v55
	v_exp_f32_e32 v55, v49
	v_add_f32_e32 v48, v48, v132
	v_add_f32_e32 v48, v134, v48
	v_exp_f32_e32 v54, v57
	v_add_f32_e32 v48, v140, v48
	v_exp_f32_e32 v57, v61
	v_add_f32_e32 v48, v124, v48
	v_mfma_f32_32x32x16_bf16 v[32:47], v[144:147], v[76:79], v[32:47]
	v_add_f32_e32 v48, v48, v55
	v_add_f32_e32 v48, v52, v48
	v_add_f32_e32 v48, v54, v48
	ds_read_b128 v[80:83], v219 offset:61440
	ds_read_b128 v[92:95], v220
	v_add_f32_e32 v89, v57, v48
	v_add_f32_e32 v48, v157, v153
	v_exp_f32_e32 v84, v51
	v_exp_f32_e32 v90, v63
	v_exp_f32_e32 v87, v60
	v_add_f32_e32 v153, v170, v48
	v_mov_b32_e32 v157, v185
	v_pk_add_f32 v[48:49], v[156:157], v[152:153]
	v_mfma_f32_32x32x16_bf16 v[32:47], v[144:147], v[72:75], v[32:47]
	v_add_f32_e64 v48, v154, v48
	v_add_f32_e64 v49, v155, v49
	v_add_f32_e64 v48, v158, v48
	v_add_f32_e64 v49, v159, v49
	v_add_f32_e64 v50, v160, v48
	v_add_f32_e64 v51, v161, v49
	s_nop 5
	v_cvt_pk_bf16_f32 v34, v69, v55
	v_cvt_pk_bf16_f32 v35, v59, v84
	v_cvt_pk_bf16_f32 v36, v71, v52
	v_cvt_pk_bf16_f32 v37, v53, v86
	v_cvt_pk_bf16_f32 v38, v85, v54
	v_cvt_pk_bf16_f32 v39, v56, v88
	v_cvt_pk_bf16_f32 v40, v87, v57
	v_cvt_pk_bf16_f32 v41, v58, v90
	s_waitcnt lgkmcnt(0)
	v_mfma_f32_32x32x16_bf16 v[0:15], v[92:95], v[34:37], v[0:15]
	ds_read_b128 v[42:45], v168 offset:61440
	ds_read_b128 v[46:49], v169
	v_mfma_f32_32x32x16_bf16 v[16:31], v[80:83], v[34:37], v[16:31]
	s_waitcnt lgkmcnt(0)
	v_mfma_f32_32x32x16_bf16 v[0:15], v[46:49], v[38:41], v[0:15]
	v_mfma_f32_32x32x16_bf16 v[16:31], v[42:45], v[38:41], v[16:31]
	v_add_f32_e64 v34, v50, v112
	v_add_f32_e64 v35, v51, v113
	v_lshlrev_b32_e32 v172, 1, v150
	v_add_f32_e64 v34, v114, v34
	v_add_f32_e64 v35, v115, v35
	s_waitcnt vmcnt(0)
	s_waitcnt lgkmcnt(0)
	s_barrier
; DI unsigned pk2(float lo, float hi) { f32x2 v = {lo, hi}; bf16x2_t b = __builtin_convertvector(v, bf16x2_t); return __builtin_bit_cast(unsigned, b); }
; DI void store_o_wide(bf16_t* rowp, const f32x16& o, float inv, int h) {
; #pragma unroll
;   for (int pr = 0; pr < 2; ++pr) {
;     const int g = 2 * pr;
;     const unsigned ax = pk2(o[4 * g] * inv, o[4 * g + 1] * inv), ay = pk2(o[4 * g + 2] * inv, o[4 * g + 3] * inv);
;     const unsigned bx = pk2(o[4 * g + 4] * inv, o[4 * g + 5] * inv), by = pk2(o[4 * g + 6] * inv, o[4 * g + 7] * inv);
;     const auto sx = __builtin_amdgcn_permlane32_swap(ax, bx, false, false);
;     const auto sy = __builtin_amdgcn_permlane32_swap(ay, by, false, false);
;     const u32x4 w = {sx[0], sy[0], sx[1], sy[1]};
;     *(u32x4*)(rowp + 8 * (g + h)) = w;
;   }
; }
; template <int TYPE, bool FIXREF>
; DI void attn_dense_unit(const Params& p, int layer, int head, int qb, char* lds, float bref) {
;     ...
;   lsum += ls0 + ls1 + ls2;
;   const float l = (NONES > 0 ? la[0] : 0.f) + lsum + __shfl_xor(lsum, 32);
;     ...
;   const float inv = 1.0f / l;
;   bf16_t* op = O + (size_t)q * 512 + head * 64;
;   store_o_wide(op, o0, inv, h); store_o_wide(op + 32, o1, inv, h);
	v_pk_add_f32 v[34:35], v[116:117], v[34:35]
	s_nop 0
	v_pk_add_f32 v[34:35], v[118:119], v[34:35]
	s_nop 0
	v_pk_add_f32 v[34:35], v[34:35], v[64:65]
	s_nop 0
	v_pk_add_f32 v[34:35], v[66:67], v[34:35]
	s_nop 0
	v_pk_add_f32 v[34:35], v[68:69], v[34:35]
	s_nop 0
	v_pk_add_f32 v[34:35], v[70:71], v[34:35]
	s_nop 0
	v_pk_add_f32 v[34:35], v[34:35], v[84:85]
	s_nop 0
	v_pk_add_f32 v[34:35], v[86:87], v[34:35]
	s_nop 0
	v_pk_add_f32 v[34:35], v[88:89], v[34:35]
	s_nop 0
	v_pk_add_f32 v[34:35], v[90:91], v[34:35]
	s_nop 0
	v_add_f32_e32 v33, v34, v35
	ds_bpermute_b32 v34, v199, v33
	v_add_f32_e32 v32, v33, v32
	s_waitcnt lgkmcnt(0)
	v_add_f32_e32 v32, v32, v34
	v_div_scale_f32 v33, s[0:1], v32, v32, 1.0
	v_rcp_f32_e32 v34, v33
	v_readlane_b32 s0, v253, 13
	v_readlane_b32 s1, v253, 14
	v_fma_f32 v35, -v33, v34, 1.0
	v_fmac_f32_e32 v34, v35, v34
	v_div_scale_f32 v35, vcc, 1.0, v32, 1.0
	v_mul_f32_e32 v36, v35, v34
	v_fma_f32 v37, -v33, v36, v35
	v_fmac_f32_e32 v36, v37, v34
	v_fma_f32 v33, -v33, v36, v35
	v_div_fmas_f32 v33, v33, v34, v36
	v_div_fixup_f32 v32, v33, v32, 1.0
	v_lshlrev_b64 v[34:35], 10, v[148:149]
	v_pk_mul_f32 v[16:17], v[16:17], v[32:33] op_sel_hi:[1,0]
	v_pk_mul_f32 v[18:19], v[18:19], v[32:33] op_sel_hi:[1,0]
	v_pk_mul_f32 v[0:1], v[0:1], v[32:33] op_sel_hi:[1,0]
	v_pk_mul_f32 v[2:3], v[2:3], v[32:33] op_sel_hi:[1,0]
	v_lshl_add_u64 v[34:35], s[0:1], 0, v[34:35]
	v_cvt_pk_bf16_f32 v16, v16, v17
	v_cvt_pk_bf16_f32 v17, v18, v19
	v_pk_mul_f32 v[18:19], v[20:21], v[32:33] op_sel_hi:[1,0]
	v_pk_mul_f32 v[20:21], v[22:23], v[32:33] op_sel_hi:[1,0]
	v_cvt_pk_bf16_f32 v0, v0, v1
	v_cvt_pk_bf16_f32 v1, v2, v3
	v_pk_mul_f32 v[2:3], v[4:5], v[32:33] op_sel_hi:[1,0]
	v_pk_mul_f32 v[4:5], v[6:7], v[32:33] op_sel_hi:[1,0]
	v_lshl_add_u64 v[34:35], v[34:35], 0, s[68:69]
	v_cvt_pk_bf16_f32 v18, v18, v19
	v_cvt_pk_bf16_f32 v19, v20, v21
	v_cvt_pk_bf16_f32 v2, v2, v3
	v_cvt_pk_bf16_f32 v3, v4, v5
	v_permlane32_swap_b32_e32 v16, v18
	v_permlane32_swap_b32_e32 v17, v19
	v_lshl_add_u64 v[20:21], v[34:35], 0, v[172:173]
	v_permlane32_swap_b32_e32 v0, v2
	v_permlane32_swap_b32_e32 v1, v3
	global_store_dwordx4 v[20:21], v[16:19], off
	global_store_dwordx4 v[20:21], v[0:3], off offset:64
	v_pk_mul_f32 v[22:23], v[30:31], v[32:33] op_sel_hi:[1,0]
	v_pk_mul_f32 v[16:17], v[24:25], v[32:33] op_sel_hi:[1,0]
	v_pk_mul_f32 v[18:19], v[26:27], v[32:33] op_sel_hi:[1,0]
	v_pk_mul_f32 v[0:1], v[8:9], v[32:33] op_sel_hi:[1,0]
	v_pk_mul_f32 v[2:3], v[10:11], v[32:33] op_sel_hi:[1,0]
	v_cvt_pk_bf16_f32 v16, v16, v17
	v_cvt_pk_bf16_f32 v17, v18, v19
	v_pk_mul_f32 v[18:19], v[28:29], v[32:33] op_sel_hi:[1,0]
	v_cvt_pk_bf16_f32 v0, v0, v1
	v_cvt_pk_bf16_f32 v1, v2, v3
	v_pk_mul_f32 v[2:3], v[12:13], v[32:33] op_sel_hi:[1,0]
	v_pk_mul_f32 v[6:7], v[14:15], v[32:33] op_sel_hi:[1,0]
	v_cvt_pk_bf16_f32 v18, v18, v19
	v_cvt_pk_bf16_f32 v19, v22, v23
	v_cvt_pk_bf16_f32 v2, v2, v3
	v_cvt_pk_bf16_f32 v3, v6, v7
	v_permlane32_swap_b32_e32 v16, v18
	v_permlane32_swap_b32_e32 v17, v19
	v_lshl_add_u64 v[4:5], v[20:21], 0, 64
	v_permlane32_swap_b32_e32 v0, v2
	v_permlane32_swap_b32_e32 v1, v3
	global_store_dwordx4 v[20:21], v[16:19], off offset:32

.Lmy_a1_norope:
	s_waitcnt lgkmcnt(0)
	v_mfma_f32_32x32x16_bf16 v[112:127], v[80:83], v[144:147], v[112:127]
	ds_read_b128 v[44:47], v202 offset:20480
	ds_read_b128 v[224:227], v202 offset:24576
	s_setprio 1
	v_exp_f32_e32 v38, v88
	v_exp_f32_e32 v43, v89
	v_exp_f32_e32 v42, v90
	v_exp_f32_e32 v39, v91
	s_setprio 0
	s_waitcnt lgkmcnt(0)
	v_mfma_f32_32x32x16_bf16 v[112:127], v[44:47], v[140:143], v[112:127]
	ds_read_b128 v[88:91], v210 offset:36864
	ds_read_b128 v[228:231], v210 offset:38912
	s_setprio 1
	v_mfma_f32_32x32x16_bf16 v[96:111], v[188:191], v[128:131], v[96:111]
	v_exp_f32_e32 v44, v92
	v_exp_f32_e32 v81, v93
	v_exp_f32_e32 v80, v94
	v_exp_f32_e32 v45, v95
	v_mfma_f32_32x32x16_bf16 v[96:111], v[220:223], v[144:147], v[96:111]
	s_setprio 0
	v_cvt_pk_bf16_f32 v92, v38, v43
	v_cvt_pk_bf16_f32 v93, v42, v39
	v_cvt_pk_bf16_f32 v94, v44, v81
	v_cvt_pk_bf16_f32 v95, v80, v45
	s_waitcnt lgkmcnt(0)
	v_mfma_f32_32x32x16_bf16 v[112:127], v[88:91], v[148:151], v[112:127]
	ds_read_b128 v[188:191], v211 offset:36864
	ds_read_b128 v[220:223], v211 offset:38912
	s_setprio 1
	v_exp_f32_e32 v46, v64
	v_exp_f32_e32 v83, v65
	v_exp_f32_e32 v82, v66
	v_exp_f32_e32 v47, v67
	s_setprio 0
	s_waitcnt lgkmcnt(0)
	v_mfma_f32_32x32x16_bf16 v[112:127], v[188:191], v[136:139], v[112:127]
	s_setprio 1
	v_mfma_f32_32x32x16_bf16 v[96:111], v[224:227], v[140:143], v[96:111]
	v_exp_f32_e32 v64, v68
	v_exp_f32_e32 v67, v69
	v_exp_f32_e32 v66, v70
	v_exp_f32_e32 v65, v71
	v_mfma_f32_32x32x16_bf16 v[96:111], v[228:231], v[148:151], v[96:111]
	s_setprio 0
	ds_read_b128 v[68:71], v206 offset:8192
	ds_read_b128 v[88:91], v206 offset:12288
	v_cvt_pk_bf16_f32 v188, v46, v83
	v_cvt_pk_bf16_f32 v189, v82, v47
	v_cvt_pk_bf16_f32 v190, v64, v67
	v_cvt_pk_bf16_f32 v191, v66, v65
	s_waitcnt lgkmcnt(0)
	v_mfma_f32_32x32x16_bf16 v[0:15], v[68:71], v[84:87], v[0:15]
	ds_read_b128 v[224:227], v205 offset:8192
	ds_read_b128 v[228:231], v205 offset:12288
	s_setprio 1
	v_exp_f32_e32 v68, v72
	v_exp_f32_e32 v71, v73
	v_exp_f32_e32 v70, v74
	v_exp_f32_e32 v69, v75
	s_setprio 0
	s_waitcnt lgkmcnt(0)
	v_mfma_f32_32x32x16_bf16 v[0:15], v[224:227], v[92:95], v[0:15]
	ds_read_b128 v[232:235], v204 offset:8192
	ds_read_b128 v[236:239], v204 offset:12288
	s_setprio 1
	v_mfma_f32_32x32x16_bf16 v[16:31], v[88:91], v[84:87], v[16:31]
	v_exp_f32_e32 v72, v76
	v_exp_f32_e32 v75, v77
	v_exp_f32_e32 v74, v78
	v_exp_f32_e32 v73, v79
	v_mfma_f32_32x32x16_bf16 v[96:111], v[220:223], v[136:139], v[96:111]
	v_mfma_f32_32x32x16_bf16 v[16:31], v[228:231], v[92:95], v[16:31]
	s_setprio 0
	v_cvt_pk_bf16_f32 v76, v68, v71
	v_cvt_pk_bf16_f32 v77, v70, v69
	v_cvt_pk_bf16_f32 v78, v72, v75
	v_cvt_pk_bf16_f32 v79, v74, v73
	s_waitcnt lgkmcnt(0)
	v_mfma_f32_32x32x16_bf16 v[0:15], v[232:235], v[188:191], v[0:15]
	ds_read_b128 v[84:87], v203 offset:8192
	ds_read_b128 v[88:91], v203 offset:12288
	v_max3_f32 v93, v114, s72, v115
	v_max3_f32 v92, v112, v113, v116
	v_max3_f32 v93, v93, v118, v119
	v_max3_f32 v92, v92, v117, v120
	v_mfma_f32_32x32x16_bf16 v[16:31], v[236:239], v[188:191], v[16:31]
	v_max3_f32 v93, v93, v122, v123
	v_max3_f32 v92, v92, v121, v124
	v_max3_f32 v93, v93, v126, v127
	s_waitcnt lgkmcnt(0)
	v_mfma_f32_32x32x16_bf16 v[0:15], v[84:87], v[76:79], v[0:15]
	v_max3_f32 v84, v92, v125, v96
	v_max3_f32 v85, v93, v98, v99
	v_max3_f32 v84, v84, v97, v100
	v_max3_f32 v85, v85, v102, v103
	v_max3_f32 v84, v84, v101, v104
	v_max3_f32 v85, v85, v106, v107
	v_max3_f32 v84, v84, v105, v108
	v_mfma_f32_32x32x16_bf16 v[16:31], v[88:91], v[76:79], v[16:31]
	v_max3_f32 v85, v85, v110, v111
	v_max3_f32 v76, v84, v109, v85
	v_mov_b32_e32 v77, v76
	s_nop 1
	v_permlane32_swap_b32_e32 v76, v77
	s_waitcnt vmcnt(2)
.LBB0_559:
.LBB0_561:
	v_pk_add_f32 v[34:35], v[184:185], v[34:35]
	v_pk_add_f32 v[36:37], v[186:187], v[36:37]
	v_pk_add_f32 v[32:33], v[32:33], v[34:35]
	v_pk_add_f32 v[36:37], v[40:41], v[36:37]
	v_pk_add_f32 v[32:33], v[38:39], v[32:33]
	v_pk_add_f32 v[36:37], v[42:43], v[36:37]
	v_pk_add_f32 v[32:33], v[44:45], v[32:33]
	v_pk_add_f32 v[36:37], v[80:81], v[36:37]
	v_pk_add_f32 v[32:33], v[46:47], v[32:33]
	v_pk_add_f32 v[36:37], v[82:83], v[36:37]
	v_pk_add_f32 v[32:33], v[64:65], v[32:33]
	v_pk_add_f32 v[36:37], v[66:67], v[36:37]
	v_pk_add_f32 v[32:33], v[68:69], v[32:33]
	s_waitcnt lgkmcnt(0)
	s_barrier
	v_pk_add_f32 v[184:185], v[72:73], v[32:33]
	v_pk_add_f32 v[36:37], v[70:71], v[36:37]
	v_max_f32_e32 v32, v76, v77
	v_pk_add_f32 v[186:187], v[74:75], v[36:37]
	v_cmp_lt_f32_e32 vcc, s96, v32
	s_cbranch_vccz .LBB0_563
	v_max_f32_e32 v32, v32, v32
	v_max_f32_e32 v33, 0, v32
	v_exp_f32_e64 v34, -v33
	v_add_f32_e32 v209, v209, v33
	v_xor_b32_e32 v32, 0x80000000, v209
	v_sub_f32_e32 v127, v127, v33
	v_sub_f32_e32 v126, v126, v33
	v_sub_f32_e32 v125, v125, v33
	v_sub_f32_e32 v124, v124, v33
	v_sub_f32_e32 v123, v123, v33
	v_sub_f32_e32 v122, v122, v33
	v_sub_f32_e32 v121, v121, v33
	v_sub_f32_e32 v120, v120, v33
	v_sub_f32_e32 v119, v119, v33
	v_sub_f32_e32 v118, v118, v33
	v_sub_f32_e32 v117, v117, v33
	v_sub_f32_e32 v116, v116, v33
	v_sub_f32_e32 v115, v115, v33
	v_sub_f32_e32 v114, v114, v33
	v_sub_f32_e32 v113, v113, v33
	v_sub_f32_e32 v112, v112, v33
	v_sub_f32_e32 v111, v111, v33
	v_sub_f32_e32 v110, v110, v33
	v_sub_f32_e32 v109, v109, v33
	v_sub_f32_e32 v108, v108, v33
	v_sub_f32_e32 v107, v107, v33
	v_sub_f32_e32 v106, v106, v33
	v_sub_f32_e32 v105, v105, v33
	v_sub_f32_e32 v104, v104, v33
	v_sub_f32_e32 v103, v103, v33
	v_sub_f32_e32 v102, v102, v33
	v_sub_f32_e32 v101, v101, v33
	v_sub_f32_e32 v100, v100, v33
	v_sub_f32_e32 v99, v99, v33
	v_sub_f32_e32 v98, v98, v33
	v_sub_f32_e32 v97, v97, v33
	v_sub_f32_e32 v96, v96, v33
	v_pk_mul_f32 v[14:15], v[14:15], v[34:35] op_sel_hi:[1,0]
	v_pk_mul_f32 v[12:13], v[12:13], v[34:35] op_sel_hi:[1,0]
	v_pk_mul_f32 v[10:11], v[10:11], v[34:35] op_sel_hi:[1,0]
	v_pk_mul_f32 v[8:9], v[8:9], v[34:35] op_sel_hi:[1,0]
	v_pk_mul_f32 v[6:7], v[6:7], v[34:35] op_sel_hi:[1,0]
	v_pk_mul_f32 v[4:5], v[4:5], v[34:35] op_sel_hi:[1,0]
	v_pk_mul_f32 v[2:3], v[2:3], v[34:35] op_sel_hi:[1,0]
	v_pk_mul_f32 v[0:1], v[0:1], v[34:35] op_sel_hi:[1,0]
	v_pk_mul_f32 v[30:31], v[30:31], v[34:35] op_sel_hi:[1,0]
	v_pk_mul_f32 v[28:29], v[28:29], v[34:35] op_sel_hi:[1,0]
	v_pk_mul_f32 v[26:27], v[26:27], v[34:35] op_sel_hi:[1,0]
	v_pk_mul_f32 v[24:25], v[24:25], v[34:35] op_sel_hi:[1,0]
	v_pk_mul_f32 v[22:23], v[22:23], v[34:35] op_sel_hi:[1,0]
	v_pk_mul_f32 v[20:21], v[20:21], v[34:35] op_sel_hi:[1,0]
	v_pk_mul_f32 v[18:19], v[18:19], v[34:35] op_sel_hi:[1,0]
	v_pk_mul_f32 v[16:17], v[16:17], v[34:35] op_sel_hi:[1,0]
	v_pk_mul_f32 v[184:185], v[184:185], v[34:35] op_sel_hi:[1,0]
	v_pk_mul_f32 v[186:187], v[186:187], v[34:35] op_sel_hi:[1,0]
	v_mov_b32_e32 v33, v32
	v_mov_b32_e32 v34, v32
	v_mov_b32_e32 v35, v32
	v_mov_b32_e32 v36, v32
	v_mov_b32_e32 v37, v32
	v_mov_b32_e32 v38, v32
	v_mov_b32_e32 v39, v32
	v_mov_b32_e32 v40, v32
	v_mov_b32_e32 v41, v32
	v_mov_b32_e32 v42, v32
	v_mov_b32_e32 v43, v32
	v_mov_b32_e32 v44, v32
	v_mov_b32_e32 v45, v32
	v_mov_b32_e32 v46, v32
	v_mov_b32_e32 v47, v32
	v_mov_b32_e32 v48, v32
	v_mov_b32_e32 v49, v32
	v_mov_b32_e32 v50, v32
	v_mov_b32_e32 v51, v32
	v_mov_b32_e32 v52, v32
	v_mov_b32_e32 v53, v32
	v_mov_b32_e32 v54, v32
	v_mov_b32_e32 v55, v32
	v_mov_b32_e32 v56, v32
	v_mov_b32_e32 v57, v32
	v_mov_b32_e32 v58, v32
	v_mov_b32_e32 v59, v32
	v_mov_b32_e32 v60, v32
	v_mov_b32_e32 v61, v32
	v_mov_b32_e32 v62, v32
	v_mov_b32_e32 v63, v32
	s_branch .LBB0_564
.LBB0_563:
.LBB0_564:
.LBB0_566:
	ds_read_b128 v[64:67], v199 offset:40960
	ds_read_b128 v[220:223], v199 offset:45056
	s_add_u32 s4, s92, 0x15658000
	s_addc_u32 s5, s93, 0
	s_mov_b32 m0, s43
	s_nop 0
	global_load_lds_dwordx4 v164, s[4:5]
	s_waitcnt lgkmcnt(0)
	v_mfma_f32_32x32x16_bf16 v[80:95], v[64:67], v[132:135], v[48:63]
	ds_read_b128 v[68:71], v200 offset:40960
	ds_read_b128 v[224:227], v200 offset:45056
	s_setprio 1
	v_exp_f32_e32 v112, v112
	v_exp_f32_e32 v189, v113
	v_exp_f32_e32 v188, v114
	v_exp_f32_e32 v113, v115
	s_setprio 0
	s_add_u32 s4, s92, 0x16618200
	s_addc_u32 s5, s93, 0
	s_mov_b32 m0, s70
	s_nop 0
	global_load_lds_dwordx4 v160, s[4:5]
	s_waitcnt lgkmcnt(0)
	v_mfma_f32_32x32x16_bf16 v[80:95], v[68:71], v[128:131], v[80:95]
	ds_read_b128 v[228:231], v201 offset:40960
	ds_read_b128 v[232:235], v201 offset:45056
	s_setprio 1
	v_mfma_f32_32x32x16_bf16 v[64:79], v[220:223], v[132:135], v[48:63]
	v_exp_f32_e32 v114, v116
	v_exp_f32_e32 v117, v117
	v_exp_f32_e32 v116, v118
	v_exp_f32_e32 v115, v119
	s_setprio 0
	v_cvt_pk_bf16_f32 v220, v112, v189
	v_cvt_pk_bf16_f32 v221, v188, v113
	v_cvt_pk_bf16_f32 v222, v114, v117
	v_cvt_pk_bf16_f32 v223, v116, v115
	s_and_b64 vcc, exec, s[44:45]
	s_cbranch_vccnz .Lmy_a2_norope
	s_add_u32 s4, s92, 0x31d8500
	s_addc_u32 s5, s93, 0
	s_add_i32 m0, s43, 0x4000
	s_nop 0
	global_load_lds_dwordx4 v162, s[4:5]
.Lmy_a2_norope:
	s_waitcnt lgkmcnt(0)
	v_mfma_f32_32x32x16_bf16 v[80:95], v[228:231], v[144:147], v[80:95]
	ds_read_b128 v[236:239], v202 offset:40960
	ds_read_b128 v[240:243], v202 offset:45056
	s_setprio 1
	v_exp_f32_e32 v118, v120
	v_exp_f32_e32 v191, v121
	v_exp_f32_e32 v190, v122
	v_exp_f32_e32 v119, v123
	s_setprio 0
	s_waitcnt lgkmcnt(0)
	v_mfma_f32_32x32x16_bf16 v[80:95], v[236:239], v[140:143], v[80:95]
	ds_read_b128 v[228:231], v210 offset:57344
	ds_read_b128 v[244:247], v210 offset:59392
	s_setprio 1
	v_mfma_f32_32x32x16_bf16 v[64:79], v[224:227], v[128:131], v[64:79]
	v_exp_f32_e32 v120, v124
	v_exp_f32_e32 v123, v125
	v_exp_f32_e32 v122, v126
	v_exp_f32_e32 v121, v127
	v_mfma_f32_32x32x16_bf16 v[64:79], v[232:235], v[144:147], v[64:79]
	s_setprio 0
	v_cvt_pk_bf16_f32 v224, v118, v191
	v_cvt_pk_bf16_f32 v225, v190, v119
	v_cvt_pk_bf16_f32 v226, v120, v123
	v_cvt_pk_bf16_f32 v227, v122, v121
	s_waitcnt lgkmcnt(0)
	v_mfma_f32_32x32x16_bf16 v[80:95], v[228:231], v[148:151], v[80:95]
	ds_read_b128 v[232:235], v211 offset:57344
	ds_read_b128 v[236:239], v211 offset:59392
	s_setprio 1
	v_exp_f32_e32 v96, v96
	v_exp_f32_e32 v125, v97
	v_exp_f32_e32 v124, v98
	v_exp_f32_e32 v97, v99
	s_setprio 0
	s_waitcnt lgkmcnt(0)
	v_mfma_f32_32x32x16_bf16 v[80:95], v[232:235], v[136:139], v[80:95]
	s_setprio 1
	v_mfma_f32_32x32x16_bf16 v[64:79], v[240:243], v[140:143], v[64:79]
	v_exp_f32_e32 v98, v100
	v_exp_f32_e32 v101, v101
	v_exp_f32_e32 v100, v102
	v_exp_f32_e32 v99, v103
	v_mfma_f32_32x32x16_bf16 v[64:79], v[244:247], v[148:151], v[64:79]
	s_setprio 0
	ds_read_b128 v[228:231], v206 offset:28672
	ds_read_b128 v[232:235], v206 offset:32768
	v_cvt_pk_bf16_f32 v240, v96, v125
	v_cvt_pk_bf16_f32 v241, v124, v97
	v_cvt_pk_bf16_f32 v242, v98, v101
	v_cvt_pk_bf16_f32 v243, v100, v99
	s_waitcnt lgkmcnt(0)
	v_mfma_f32_32x32x16_bf16 v[0:15], v[228:231], v[220:223], v[0:15]
	ds_read_b128 v[244:247], v205 offset:28672
	ds_read_b128 v[180:183], v205 offset:32768
	s_setprio 1
	v_exp_f32_e32 v102, v104
	v_exp_f32_e32 v105, v105
	v_exp_f32_e32 v104, v106
	v_exp_f32_e32 v103, v107
	s_setprio 0
	s_waitcnt lgkmcnt(0)
	v_mfma_f32_32x32x16_bf16 v[0:15], v[244:247], v[224:227], v[0:15]
	ds_read_b128 v[228:231], v204 offset:28672
	ds_read_b128 v[174:177], v204 offset:32768
	s_setprio 1
	v_mfma_f32_32x32x16_bf16 v[16:31], v[232:235], v[220:223], v[16:31]
	v_exp_f32_e32 v106, v108
	v_exp_f32_e32 v109, v109
	v_exp_f32_e32 v108, v110
	v_exp_f32_e32 v107, v111
	v_mfma_f32_32x32x16_bf16 v[64:79], v[236:239], v[136:139], v[64:79]
	v_mfma_f32_32x32x16_bf16 v[16:31], v[180:183], v[224:227], v[16:31]
	s_setprio 0
	v_cvt_pk_bf16_f32 v180, v102, v105
	v_cvt_pk_bf16_f32 v181, v104, v103
	v_cvt_pk_bf16_f32 v182, v106, v109
	v_cvt_pk_bf16_f32 v183, v108, v107
	s_waitcnt lgkmcnt(0)
	v_mfma_f32_32x32x16_bf16 v[0:15], v[228:231], v[240:243], v[0:15]
	ds_read_b128 v[220:223], v203 offset:28672
	ds_read_b128 v[224:227], v203 offset:32768
	v_max3_f32 v111, v82, s72, v83
	v_max3_f32 v110, v80, v81, v84
	v_max3_f32 v111, v111, v86, v87
	v_max3_f32 v110, v110, v85, v88
	v_mfma_f32_32x32x16_bf16 v[16:31], v[174:177], v[240:243], v[16:31]
	v_max3_f32 v111, v111, v90, v91
	v_max3_f32 v110, v110, v89, v92
	v_max3_f32 v111, v111, v94, v95
	s_waitcnt lgkmcnt(0)
	v_mfma_f32_32x32x16_bf16 v[0:15], v[220:223], v[180:183], v[0:15]
	v_max3_f32 v110, v110, v93, v64
	v_max3_f32 v111, v111, v66, v67
	v_max3_f32 v110, v110, v65, v68
	v_max3_f32 v111, v111, v70, v71
	v_max3_f32 v110, v110, v69, v72
	v_max3_f32 v111, v111, v74, v75
	v_max3_f32 v110, v110, v73, v76
	v_mfma_f32_32x32x16_bf16 v[16:31], v[224:227], v[180:183], v[16:31]
	v_max3_f32 v111, v111, v78, v79
	v_max3_f32 v110, v110, v77, v111
	v_mov_b32_e32 v111, v110
	s_nop 1
	v_permlane32_swap_b32_e32 v110, v111
	s_waitcnt vmcnt(2)
.LBB0_568:
.LBB0_570:
	v_pk_add_f32 v[126:127], v[186:187], v[188:189]
	v_pk_add_f32 v[112:113], v[112:113], v[184:185]
	v_pk_add_f32 v[116:117], v[116:117], v[126:127]
	v_pk_add_f32 v[112:113], v[114:115], v[112:113]
	v_pk_add_f32 v[116:117], v[190:191], v[116:117]
	v_pk_add_f32 v[112:113], v[118:119], v[112:113]
	v_pk_add_f32 v[114:115], v[122:123], v[116:117]
	s_waitcnt lgkmcnt(0)
	s_barrier
	v_pk_add_f32 v[114:115], v[124:125], v[114:115]
	s_nop 0
	v_pk_add_f32 v[100:101], v[100:101], v[114:115]
	s_nop 0
	v_pk_add_f32 v[100:101], v[104:105], v[100:101]
	v_pk_add_f32 v[104:105], v[120:121], v[112:113]
	v_pk_add_f32 v[186:187], v[108:109], v[100:101]
	v_pk_add_f32 v[96:97], v[96:97], v[104:105]
	s_nop 0
	v_pk_add_f32 v[96:97], v[98:99], v[96:97]
	s_nop 0
	v_pk_add_f32 v[96:97], v[102:103], v[96:97]
	s_nop 0
	v_pk_add_f32 v[184:185], v[106:107], v[96:97]
	v_max_f32_e32 v96, v110, v111
	v_cmp_lt_f32_e32 vcc, s96, v96
	s_cbranch_vccz .LBB0_572
	v_max_f32_e32 v32, v96, v96
	v_max_f32_e32 v33, 0, v32
	v_exp_f32_e64 v34, -v33
	v_add_f32_e32 v209, v209, v33
	v_xor_b32_e32 v32, 0x80000000, v209
	v_sub_f32_e32 v95, v95, v33
	v_sub_f32_e32 v94, v94, v33
	v_sub_f32_e32 v93, v93, v33
	v_sub_f32_e32 v92, v92, v33
	v_sub_f32_e32 v91, v91, v33
	v_sub_f32_e32 v90, v90, v33
	v_sub_f32_e32 v89, v89, v33
	v_sub_f32_e32 v88, v88, v33
	v_sub_f32_e32 v87, v87, v33
	v_sub_f32_e32 v86, v86, v33
	v_sub_f32_e32 v85, v85, v33
	v_sub_f32_e32 v84, v84, v33
	v_sub_f32_e32 v83, v83, v33
	v_sub_f32_e32 v82, v82, v33
	v_sub_f32_e32 v81, v81, v33
	v_sub_f32_e32 v80, v80, v33
	v_sub_f32_e32 v79, v79, v33
	v_sub_f32_e32 v78, v78, v33
	v_sub_f32_e32 v77, v77, v33
	v_sub_f32_e32 v76, v76, v33
	v_sub_f32_e32 v75, v75, v33
	v_sub_f32_e32 v74, v74, v33
	v_sub_f32_e32 v73, v73, v33
	v_sub_f32_e32 v72, v72, v33
	v_sub_f32_e32 v71, v71, v33
	v_sub_f32_e32 v70, v70, v33
	v_sub_f32_e32 v69, v69, v33
	v_sub_f32_e32 v68, v68, v33
	v_sub_f32_e32 v67, v67, v33
	v_sub_f32_e32 v66, v66, v33
	v_sub_f32_e32 v65, v65, v33
	v_sub_f32_e32 v64, v64, v33
	v_pk_mul_f32 v[14:15], v[14:15], v[34:35] op_sel_hi:[1,0]
	v_pk_mul_f32 v[12:13], v[12:13], v[34:35] op_sel_hi:[1,0]
	v_pk_mul_f32 v[10:11], v[10:11], v[34:35] op_sel_hi:[1,0]
	v_pk_mul_f32 v[8:9], v[8:9], v[34:35] op_sel_hi:[1,0]
	v_pk_mul_f32 v[6:7], v[6:7], v[34:35] op_sel_hi:[1,0]
	v_pk_mul_f32 v[4:5], v[4:5], v[34:35] op_sel_hi:[1,0]
	v_pk_mul_f32 v[2:3], v[2:3], v[34:35] op_sel_hi:[1,0]
	v_pk_mul_f32 v[0:1], v[0:1], v[34:35] op_sel_hi:[1,0]
	v_pk_mul_f32 v[30:31], v[30:31], v[34:35] op_sel_hi:[1,0]
	v_pk_mul_f32 v[28:29], v[28:29], v[34:35] op_sel_hi:[1,0]
	v_pk_mul_f32 v[26:27], v[26:27], v[34:35] op_sel_hi:[1,0]
	v_pk_mul_f32 v[24:25], v[24:25], v[34:35] op_sel_hi:[1,0]
	v_pk_mul_f32 v[22:23], v[22:23], v[34:35] op_sel_hi:[1,0]
	v_pk_mul_f32 v[20:21], v[20:21], v[34:35] op_sel_hi:[1,0]
	v_pk_mul_f32 v[18:19], v[18:19], v[34:35] op_sel_hi:[1,0]
	v_pk_mul_f32 v[16:17], v[16:17], v[34:35] op_sel_hi:[1,0]
	v_pk_mul_f32 v[184:185], v[184:185], v[34:35] op_sel_hi:[1,0]
	v_pk_mul_f32 v[186:187], v[186:187], v[34:35] op_sel_hi:[1,0]
	v_mov_b32_e32 v33, v32
	v_mov_b32_e32 v34, v32
	v_mov_b32_e32 v35, v32
	v_mov_b32_e32 v36, v32
	v_mov_b32_e32 v37, v32
	v_mov_b32_e32 v38, v32
	v_mov_b32_e32 v39, v32
	v_mov_b32_e32 v40, v32
	v_mov_b32_e32 v41, v32
	v_mov_b32_e32 v42, v32
	v_mov_b32_e32 v43, v32
	v_mov_b32_e32 v44, v32
	v_mov_b32_e32 v45, v32
	v_mov_b32_e32 v46, v32
	v_mov_b32_e32 v47, v32
	v_mov_b32_e32 v48, v32
	v_mov_b32_e32 v49, v32
	v_mov_b32_e32 v50, v32
	v_mov_b32_e32 v51, v32
	v_mov_b32_e32 v52, v32
	v_mov_b32_e32 v53, v32
	v_mov_b32_e32 v54, v32
	v_mov_b32_e32 v55, v32
	v_mov_b32_e32 v56, v32
	v_mov_b32_e32 v57, v32
	v_mov_b32_e32 v58, v32
	v_mov_b32_e32 v59, v32
	v_mov_b32_e32 v60, v32
	v_mov_b32_e32 v61, v32
	v_mov_b32_e32 v62, v32
	v_mov_b32_e32 v63, v32
.LBB0_572:
.LBB0_574:
	s_add_i32 s10, 0, 0x10000
	v_add_u32_e32 v172, s10, v212
	ds_read_b128 v[96:99], v199 offset:61440
	ds_read_b128 v[174:177], v172
	s_add_u32 s4, s92, 0x15668000
	s_addc_u32 s5, s93, 0
	s_mov_b32 m0, s71
	s_nop 0
	global_load_lds_dwordx4 v164, s[4:5]
	s_waitcnt lgkmcnt(0)
	v_mfma_f32_32x32x16_bf16 v[112:127], v[96:99], v[132:135], v[48:63]
	v_add_u32_e32 v220, s10, v214
	ds_read_b128 v[100:103], v200 offset:61440
	ds_read_b128 v[180:183], v220
	s_setprio 1
	v_exp_f32_e32 v80, v80
	v_exp_f32_e32 v189, v81
	v_exp_f32_e32 v188, v82
	v_exp_f32_e32 v81, v83
	s_setprio 0
	s_add_u32 s4, s92, 0x16618280
	s_addc_u32 s5, s93, 0
	s_mov_b32 m0, s90
	s_nop 0
	global_load_lds_dwordx4 v160, s[4:5]
	s_waitcnt lgkmcnt(0)
	v_mfma_f32_32x32x16_bf16 v[112:127], v[100:103], v[128:131], v[112:127]
	v_add_u32_e32 v221, s10, v216
	ds_read_b128 v[224:227], v201 offset:61440
	ds_read_b128 v[228:231], v221
	s_setprio 1
	v_mfma_f32_32x32x16_bf16 v[96:111], v[174:177], v[132:135], v[48:63]
	v_exp_f32_e32 v82, v84
	v_exp_f32_e32 v191, v85
	v_exp_f32_e32 v190, v86
	v_exp_f32_e32 v83, v87
	s_setprio 0
	v_cvt_pk_bf16_f32 v174, v80, v189
	v_cvt_pk_bf16_f32 v175, v188, v81
	v_cvt_pk_bf16_f32 v176, v82, v191
	v_cvt_pk_bf16_f32 v177, v190, v83
	s_and_b64 vcc, exec, s[44:45]
	s_cbranch_vccnz .Lmy_a3_norope
	s_add_u32 s4, s92, 0x32c8500
	s_addc_u32 s5, s93, 0
	s_add_i32 m0, s43, 0x9000
	s_nop 0
	global_load_lds_dwordx4 v162, s[4:5]
.Lmy_a3_norope:
	s_waitcnt lgkmcnt(0)
	v_mfma_f32_32x32x16_bf16 v[112:127], v[224:227], v[144:147], v[112:127]
	v_add_u32_e32 v222, s10, v218
	ds_read_b128 v[232:235], v202 offset:61440
	ds_read_b128 v[236:239], v222
	s_setprio 1
	v_exp_f32_e32 v84, v88
	v_exp_f32_e32 v87, v89
	v_exp_f32_e32 v86, v90
	v_exp_f32_e32 v85, v91
	s_setprio 0
	s_waitcnt lgkmcnt(0)
	v_mfma_f32_32x32x16_bf16 v[112:127], v[232:235], v[140:143], v[112:127]
	ds_read_b128 v[224:227], v208 offset:61440
	ds_read_b128 v[240:243], v208 offset:63488
	s_setprio 1
	v_mfma_f32_32x32x16_bf16 v[96:111], v[180:183], v[128:131], v[96:111]
	v_exp_f32_e32 v88, v92
	v_exp_f32_e32 v91, v93
	v_exp_f32_e32 v90, v94
	v_exp_f32_e32 v89, v95
	v_mfma_f32_32x32x16_bf16 v[96:111], v[228:231], v[144:147], v[96:111]
	s_setprio 0
	v_cvt_pk_bf16_f32 v180, v84, v87
	v_cvt_pk_bf16_f32 v181, v86, v85
	v_cvt_pk_bf16_f32 v182, v88, v91
	v_cvt_pk_bf16_f32 v183, v90, v89
	s_waitcnt lgkmcnt(0)
	v_mfma_f32_32x32x16_bf16 v[112:127], v[224:227], v[148:151], v[112:127]
	ds_read_b128 v[228:231], v207 offset:61440
	ds_read_b128 v[232:235], v207 offset:63488
	s_setprio 1
	v_exp_f32_e32 v64, v64
	v_exp_f32_e32 v93, v65
	v_exp_f32_e32 v92, v66
	v_exp_f32_e32 v65, v67
	s_setprio 0
	s_waitcnt lgkmcnt(0)
	v_mfma_f32_32x32x16_bf16 v[112:127], v[228:231], v[136:139], v[112:127]
	s_setprio 1
	v_mfma_f32_32x32x16_bf16 v[96:111], v[236:239], v[140:143], v[96:111]
	v_exp_f32_e32 v66, v68
	v_exp_f32_e32 v69, v69
	v_exp_f32_e32 v68, v70
	v_exp_f32_e32 v67, v71
	v_mfma_f32_32x32x16_bf16 v[96:111], v[240:243], v[148:151], v[96:111]
	s_setprio 0
	ds_read_b128 v[224:227], v206 offset:49152
	ds_read_b128 v[228:231], v206 offset:53248
	v_cvt_pk_bf16_f32 v236, v64, v93
	v_cvt_pk_bf16_f32 v237, v92, v65
	v_cvt_pk_bf16_f32 v238, v66, v69
	v_cvt_pk_bf16_f32 v239, v68, v67
	s_waitcnt lgkmcnt(0)
	v_mfma_f32_32x32x16_bf16 v[0:15], v[224:227], v[174:177], v[0:15]
	ds_read_b128 v[240:243], v205 offset:49152
	ds_read_b128 v[244:247], v205 offset:53248
	s_setprio 1
	v_exp_f32_e32 v70, v72
	v_exp_f32_e32 v73, v73
	v_exp_f32_e32 v72, v74
	v_exp_f32_e32 v71, v75
	s_setprio 0
	s_waitcnt lgkmcnt(0)
	v_mfma_f32_32x32x16_bf16 v[0:15], v[240:243], v[180:183], v[0:15]
	ds_read_b128 v[224:227], v204 offset:49152
	ds_read_b128 v[192:195], v204 offset:53248
	s_setprio 1
	v_mfma_f32_32x32x16_bf16 v[16:31], v[228:231], v[174:177], v[16:31]
	v_exp_f32_e32 v74, v76
	v_exp_f32_e32 v77, v77
	v_exp_f32_e32 v76, v78
	v_exp_f32_e32 v75, v79
	v_mfma_f32_32x32x16_bf16 v[96:111], v[232:235], v[136:139], v[96:111]
	v_mfma_f32_32x32x16_bf16 v[16:31], v[244:247], v[180:183], v[16:31]
	s_setprio 0
	v_cvt_pk_bf16_f32 v174, v70, v73
	v_cvt_pk_bf16_f32 v175, v72, v71
	v_cvt_pk_bf16_f32 v176, v74, v77
	v_cvt_pk_bf16_f32 v177, v76, v75
	s_waitcnt lgkmcnt(0)
	v_mfma_f32_32x32x16_bf16 v[0:15], v[224:227], v[236:239], v[0:15]
	ds_read_b128 v[180:183], v203 offset:49152
	ds_read_b128 v[228:231], v203 offset:53248
	v_max3_f32 v79, v114, s72, v115
	v_max3_f32 v78, v112, v113, v116
	v_max3_f32 v79, v79, v118, v119
	v_max3_f32 v78, v78, v117, v120
	v_mfma_f32_32x32x16_bf16 v[16:31], v[192:195], v[236:239], v[16:31]
	v_max3_f32 v79, v79, v122, v123
	v_max3_f32 v78, v78, v121, v124
	v_max3_f32 v79, v79, v126, v127
	s_waitcnt lgkmcnt(0)
	v_mfma_f32_32x32x16_bf16 v[0:15], v[180:183], v[174:177], v[0:15]
	v_max3_f32 v78, v78, v125, v96
	v_max3_f32 v79, v79, v98, v99
	v_max3_f32 v78, v78, v97, v100
	v_max3_f32 v79, v79, v102, v103
	v_max3_f32 v78, v78, v101, v104
	v_max3_f32 v79, v79, v106, v107
	v_max3_f32 v78, v78, v105, v108
	v_mfma_f32_32x32x16_bf16 v[16:31], v[228:231], v[174:177], v[16:31]
	v_max3_f32 v79, v79, v110, v111
	v_max3_f32 v78, v78, v109, v79
	v_mov_b32_e32 v79, v78
	s_nop 1
	v_permlane32_swap_b32_e32 v78, v79
	s_waitcnt vmcnt(2)
.LBB0_576:
.LBB0_578:
	v_pk_add_f32 v[80:81], v[80:81], v[184:185]
	v_pk_add_f32 v[94:95], v[186:187], v[188:189]
	v_pk_add_f32 v[80:81], v[82:83], v[80:81]
	v_pk_add_f32 v[94:95], v[190:191], v[94:95]
	v_pk_add_f32 v[80:81], v[84:85], v[80:81]
	v_pk_add_f32 v[86:87], v[86:87], v[94:95]
	v_pk_add_f32 v[80:81], v[88:89], v[80:81]
	v_pk_add_f32 v[86:87], v[90:91], v[86:87]
	v_pk_add_f32 v[64:65], v[64:65], v[80:81]
	v_pk_add_f32 v[86:87], v[92:93], v[86:87]
	v_pk_add_f32 v[64:65], v[66:67], v[64:65]
	v_pk_add_f32 v[68:69], v[68:69], v[86:87]
	v_pk_add_f32 v[64:65], v[70:71], v[64:65]
	s_waitcnt lgkmcnt(0)
	s_barrier
	v_pk_add_f32 v[184:185], v[74:75], v[64:65]
	v_pk_add_f32 v[68:69], v[72:73], v[68:69]
	v_max_f32_e32 v64, v78, v79
	v_pk_add_f32 v[186:187], v[76:77], v[68:69]
	v_cmp_lt_f32_e32 vcc, s96, v64
	s_cbranch_vccz .LBB0_580
	v_max_f32_e32 v32, v64, v64
	v_max_f32_e32 v33, 0, v32
	v_exp_f32_e64 v34, -v33
	v_add_f32_e32 v209, v209, v33
	v_xor_b32_e32 v32, 0x80000000, v209
	v_sub_f32_e32 v127, v127, v33
	v_sub_f32_e32 v126, v126, v33
	v_sub_f32_e32 v125, v125, v33
	v_sub_f32_e32 v124, v124, v33
	v_sub_f32_e32 v123, v123, v33
	v_sub_f32_e32 v122, v122, v33
	v_sub_f32_e32 v121, v121, v33
	v_sub_f32_e32 v120, v120, v33
	v_sub_f32_e32 v119, v119, v33
	v_sub_f32_e32 v118, v118, v33
	v_sub_f32_e32 v117, v117, v33
	v_sub_f32_e32 v116, v116, v33
	v_sub_f32_e32 v115, v115, v33
	v_sub_f32_e32 v114, v114, v33
	v_sub_f32_e32 v113, v113, v33
	v_sub_f32_e32 v112, v112, v33
	v_sub_f32_e32 v111, v111, v33
	v_sub_f32_e32 v110, v110, v33
	v_sub_f32_e32 v109, v109, v33
	v_sub_f32_e32 v108, v108, v33
	v_sub_f32_e32 v107, v107, v33
	v_sub_f32_e32 v106, v106, v33
	v_sub_f32_e32 v105, v105, v33
	v_sub_f32_e32 v104, v104, v33
	v_sub_f32_e32 v103, v103, v33
	v_sub_f32_e32 v102, v102, v33
	v_sub_f32_e32 v101, v101, v33
	v_sub_f32_e32 v100, v100, v33
	v_sub_f32_e32 v99, v99, v33
	v_sub_f32_e32 v98, v98, v33
	v_sub_f32_e32 v97, v97, v33
	v_sub_f32_e32 v96, v96, v33
	v_pk_mul_f32 v[14:15], v[14:15], v[34:35] op_sel_hi:[1,0]
	v_pk_mul_f32 v[12:13], v[12:13], v[34:35] op_sel_hi:[1,0]
	v_pk_mul_f32 v[10:11], v[10:11], v[34:35] op_sel_hi:[1,0]
	v_pk_mul_f32 v[8:9], v[8:9], v[34:35] op_sel_hi:[1,0]
	v_pk_mul_f32 v[6:7], v[6:7], v[34:35] op_sel_hi:[1,0]
	v_pk_mul_f32 v[4:5], v[4:5], v[34:35] op_sel_hi:[1,0]
	v_pk_mul_f32 v[2:3], v[2:3], v[34:35] op_sel_hi:[1,0]
	v_pk_mul_f32 v[0:1], v[0:1], v[34:35] op_sel_hi:[1,0]
	v_pk_mul_f32 v[30:31], v[30:31], v[34:35] op_sel_hi:[1,0]
	v_pk_mul_f32 v[28:29], v[28:29], v[34:35] op_sel_hi:[1,0]
	v_pk_mul_f32 v[26:27], v[26:27], v[34:35] op_sel_hi:[1,0]
	v_pk_mul_f32 v[24:25], v[24:25], v[34:35] op_sel_hi:[1,0]
	v_pk_mul_f32 v[22:23], v[22:23], v[34:35] op_sel_hi:[1,0]
	v_pk_mul_f32 v[20:21], v[20:21], v[34:35] op_sel_hi:[1,0]
	v_pk_mul_f32 v[18:19], v[18:19], v[34:35] op_sel_hi:[1,0]
	v_pk_mul_f32 v[16:17], v[16:17], v[34:35] op_sel_hi:[1,0]
	v_pk_mul_f32 v[184:185], v[184:185], v[34:35] op_sel_hi:[1,0]
	v_pk_mul_f32 v[186:187], v[186:187], v[34:35] op_sel_hi:[1,0]
	v_mov_b32_e32 v33, v32
	v_mov_b32_e32 v34, v32
	v_mov_b32_e32 v35, v32
	v_mov_b32_e32 v36, v32
	v_mov_b32_e32 v37, v32
	v_mov_b32_e32 v38, v32
	v_mov_b32_e32 v39, v32
	v_mov_b32_e32 v40, v32
	v_mov_b32_e32 v41, v32
	v_mov_b32_e32 v42, v32
	v_mov_b32_e32 v43, v32
	v_mov_b32_e32 v44, v32
	v_mov_b32_e32 v45, v32
	v_mov_b32_e32 v46, v32
	v_mov_b32_e32 v47, v32
	v_mov_b32_e32 v48, v32
	v_mov_b32_e32 v49, v32
	v_mov_b32_e32 v50, v32
	v_mov_b32_e32 v51, v32
	v_mov_b32_e32 v52, v32
	v_mov_b32_e32 v53, v32
	v_mov_b32_e32 v54, v32
	v_mov_b32_e32 v55, v32
	v_mov_b32_e32 v56, v32
	v_mov_b32_e32 v57, v32
	v_mov_b32_e32 v58, v32
	v_mov_b32_e32 v59, v32
	v_mov_b32_e32 v60, v32
	v_mov_b32_e32 v61, v32
	v_mov_b32_e32 v62, v32
	v_mov_b32_e32 v63, v32
.LBB0_580:
.LBB0_582:
	ds_read_b128 v[64:67], v199
	ds_read_b128 v[174:177], v199 offset:4096
	s_add_u32 s4, s92, 0x15678000
	s_addc_u32 s5, s93, 0
	s_mov_b32 m0, s91
	s_nop 0
	global_load_lds_dwordx4 v164, s[4:5]
	s_waitcnt lgkmcnt(0)
	v_mfma_f32_32x32x16_bf16 v[80:95], v[64:67], v[132:135], v[48:63]
	ds_read_b128 v[68:71], v200
	ds_read_b128 v[180:183], v200 offset:4096
	s_setprio 1
	v_exp_f32_e32 v112, v112
	v_exp_f32_e32 v167, v113
	v_exp_f32_e32 v166, v114
	v_exp_f32_e32 v113, v115
	s_setprio 0
	s_add_u32 s4, s92, 0x16618300
	s_addc_u32 s5, s93, 0
	s_mov_b32 m0, s95
	s_nop 0
	global_load_lds_dwordx4 v160, s[4:5]
	s_waitcnt lgkmcnt(0)
	v_mfma_f32_32x32x16_bf16 v[80:95], v[68:71], v[128:131], v[80:95]
	ds_read_b128 v[188:191], v201
	ds_read_b128 v[192:195], v201 offset:4096
	s_setprio 1
	v_mfma_f32_32x32x16_bf16 v[64:79], v[174:177], v[132:135], v[48:63]
	v_exp_f32_e32 v114, v116
	v_exp_f32_e32 v169, v117
	v_exp_f32_e32 v168, v118
	v_exp_f32_e32 v115, v119
	s_setprio 0
	v_cvt_pk_bf16_f32 v174, v112, v167
	v_cvt_pk_bf16_f32 v175, v166, v113
	v_cvt_pk_bf16_f32 v176, v114, v169
	v_cvt_pk_bf16_f32 v177, v168, v115
	s_and_b64 vcc, exec, s[44:45]
	s_cbranch_vccnz .Lmy_a4_norope
	s_add_u32 s4, s92, 0x33b8500
	s_addc_u32 s5, s93, 0
	s_add_i32 m0, s43, 0xe000
	s_nop 0
	global_load_lds_dwordx4 v162, s[4:5]
.Lmy_a4_norope:
	s_waitcnt lgkmcnt(0)
	v_mfma_f32_32x32x16_bf16 v[80:95], v[188:191], v[144:147], v[80:95]
	ds_read_b128 v[224:227], v202
	ds_read_b128 v[228:231], v202 offset:4096
	s_setprio 1
	v_exp_f32_e32 v116, v120
	v_exp_f32_e32 v121, v121
	v_exp_f32_e32 v120, v122
	v_exp_f32_e32 v117, v123
	s_setprio 0
	s_waitcnt lgkmcnt(0)
	v_mfma_f32_32x32x16_bf16 v[80:95], v[224:227], v[140:143], v[80:95]
	ds_read_b128 v[188:191], v210 offset:16384
	ds_read_b128 v[232:235], v210 offset:18432
	s_setprio 1
	v_mfma_f32_32x32x16_bf16 v[64:79], v[180:183], v[128:131], v[64:79]
	v_exp_f32_e32 v118, v124
	v_exp_f32_e32 v123, v125
	v_exp_f32_e32 v122, v126
	v_exp_f32_e32 v119, v127
	v_mfma_f32_32x32x16_bf16 v[64:79], v[192:195], v[144:147], v[64:79]
	s_setprio 0
	v_cvt_pk_bf16_f32 v180, v116, v121
	v_cvt_pk_bf16_f32 v181, v120, v117
	v_cvt_pk_bf16_f32 v182, v118, v123
	v_cvt_pk_bf16_f32 v183, v122, v119
	s_waitcnt lgkmcnt(0)
	v_mfma_f32_32x32x16_bf16 v[80:95], v[188:191], v[148:151], v[80:95]
	ds_read_b128 v[192:195], v211 offset:16384
	ds_read_b128 v[224:227], v211 offset:18432
	s_setprio 1
	v_exp_f32_e32 v96, v96
	v_exp_f32_e32 v125, v97
	v_exp_f32_e32 v124, v98
	v_exp_f32_e32 v97, v99
	s_setprio 0
	s_waitcnt lgkmcnt(0)
	v_mfma_f32_32x32x16_bf16 v[80:95], v[192:195], v[136:139], v[80:95]
	s_setprio 1
	v_mfma_f32_32x32x16_bf16 v[64:79], v[228:231], v[140:143], v[64:79]
	v_exp_f32_e32 v98, v100
	v_exp_f32_e32 v101, v101
	v_exp_f32_e32 v100, v102
	v_exp_f32_e32 v99, v103
	v_mfma_f32_32x32x16_bf16 v[64:79], v[232:235], v[148:151], v[64:79]
	s_setprio 0
	v_add_u32_e32 v170, 0, v213
	v_add_u32_e32 v171, s10, v213
	ds_read_b128 v[190:193], v170 offset:61440
	ds_read_b128 v[228:231], v171
	v_cvt_pk_bf16_f32 v232, v96, v125
	v_cvt_pk_bf16_f32 v233, v124, v97
	v_cvt_pk_bf16_f32 v234, v98, v101
	v_cvt_pk_bf16_f32 v235, v100, v99
	s_waitcnt lgkmcnt(0)
	v_mfma_f32_32x32x16_bf16 v[0:15], v[190:193], v[174:177], v[0:15]
	v_add_u32_e32 v188, 0, v215
	v_add_u32_e32 v189, s10, v215
	ds_read_b128 v[236:239], v188 offset:61440
	ds_read_b128 v[240:243], v189
	s_setprio 1
	v_exp_f32_e32 v102, v104
	v_exp_f32_e32 v105, v105
	v_exp_f32_e32 v104, v106
	v_exp_f32_e32 v103, v107
	s_setprio 0
	s_waitcnt lgkmcnt(0)
	v_mfma_f32_32x32x16_bf16 v[0:15], v[236:239], v[180:183], v[0:15]
	v_add_u32_e32 v190, 0, v217
	v_add_u32_e32 v191, s10, v217
	ds_read_b128 v[192:195], v190 offset:61440
	ds_read_b128 v[244:247], v191
	s_setprio 1
	v_mfma_f32_32x32x16_bf16 v[16:31], v[228:231], v[174:177], v[16:31]
	v_exp_f32_e32 v106, v108
	v_exp_f32_e32 v109, v109
	v_exp_f32_e32 v108, v110
	v_exp_f32_e32 v107, v111
	v_mfma_f32_32x32x16_bf16 v[64:79], v[224:227], v[136:139], v[64:79]
	v_mfma_f32_32x32x16_bf16 v[16:31], v[240:243], v[180:183], v[16:31]
	s_setprio 0
	v_cvt_pk_bf16_f32 v174, v102, v105
	v_cvt_pk_bf16_f32 v175, v104, v103
	v_cvt_pk_bf16_f32 v176, v106, v109
	v_cvt_pk_bf16_f32 v177, v108, v107
	s_waitcnt lgkmcnt(0)
	v_mfma_f32_32x32x16_bf16 v[0:15], v[192:195], v[232:235], v[0:15]
	v_add_u32_e32 v126, 0, v219
	v_add_u32_e32 v127, s10, v219
	ds_read_b128 v[180:183], v126 offset:61440
	ds_read_b128 v[224:227], v127
	v_max3_f32 v111, v82, s72, v83
	v_mfma_f32_32x32x16_bf16 v[16:31], v[244:247], v[232:235], v[16:31]
	v_max3_f32 v110, v80, v81, v84
	v_max3_f32 v111, v111, v86, v87
	v_max3_f32 v110, v110, v85, v88
	v_max3_f32 v111, v111, v90, v91
	v_max3_f32 v110, v110, v89, v92
	v_max3_f32 v111, v111, v94, v95
	s_waitcnt lgkmcnt(0)
	v_mfma_f32_32x32x16_bf16 v[0:15], v[180:183], v[174:177], v[0:15]
	v_max3_f32 v110, v110, v93, v64
	v_max3_f32 v111, v111, v66, v67
	v_max3_f32 v110, v110, v65, v68
	v_max3_f32 v111, v111, v70, v71
	v_max3_f32 v110, v110, v69, v72
	v_max3_f32 v111, v111, v74, v75
	v_max3_f32 v110, v110, v73, v76
	v_mfma_f32_32x32x16_bf16 v[16:31], v[224:227], v[174:177], v[16:31]
	v_max3_f32 v111, v111, v78, v79
	v_max3_f32 v110, v110, v77, v111
	v_mov_b32_e32 v111, v110
	s_nop 1
	v_permlane32_swap_b32_e32 v110, v111
	s_waitcnt vmcnt(2)
.LBB0_584:
.LBB0_586:
	v_pk_add_f32 v[166:167], v[186:187], v[166:167]
	s_waitcnt lgkmcnt(0)
	s_barrier
	v_pk_add_f32 v[166:167], v[168:169], v[166:167]
	s_nop 0
	v_pk_add_f32 v[120:121], v[120:121], v[166:167]
	s_nop 0
	v_pk_add_f32 v[120:121], v[122:123], v[120:121]
	s_nop 0
	v_pk_add_f32 v[120:121], v[124:125], v[120:121]
	s_nop 0
	v_pk_add_f32 v[100:101], v[100:101], v[120:121]
	s_nop 0
	v_pk_add_f32 v[100:101], v[104:105], v[100:101]
	v_pk_add_f32 v[104:105], v[112:113], v[184:185]
	v_pk_add_f32 v[186:187], v[108:109], v[100:101]
	v_pk_add_f32 v[104:105], v[114:115], v[104:105]
	s_nop 0
	v_pk_add_f32 v[104:105], v[116:117], v[104:105]
	s_nop 0
	v_pk_add_f32 v[104:105], v[118:119], v[104:105]
	s_nop 0
	v_pk_add_f32 v[96:97], v[96:97], v[104:105]
	s_nop 0
	v_pk_add_f32 v[96:97], v[98:99], v[96:97]
	s_nop 0
	v_pk_add_f32 v[96:97], v[102:103], v[96:97]
	s_nop 0
	v_pk_add_f32 v[184:185], v[106:107], v[96:97]
	v_max_f32_e32 v96, v110, v111
	v_cmp_lt_f32_e32 vcc, s96, v96
	s_cbranch_vccz .LBB0_554
	v_max_f32_e32 v32, v96, v96
	v_max_f32_e32 v33, 0, v32
	v_exp_f32_e64 v34, -v33
	v_add_f32_e32 v209, v209, v33
	v_xor_b32_e32 v32, 0x80000000, v209
	v_sub_f32_e32 v95, v95, v33
	v_sub_f32_e32 v94, v94, v33
	v_sub_f32_e32 v93, v93, v33
	v_sub_f32_e32 v92, v92, v33
	v_sub_f32_e32 v91, v91, v33
	v_sub_f32_e32 v90, v90, v33
	v_sub_f32_e32 v89, v89, v33
	v_sub_f32_e32 v88, v88, v33
	v_sub_f32_e32 v87, v87, v33
	v_sub_f32_e32 v86, v86, v33
	v_sub_f32_e32 v85, v85, v33
	v_sub_f32_e32 v84, v84, v33
	v_sub_f32_e32 v83, v83, v33
	v_sub_f32_e32 v82, v82, v33
	v_sub_f32_e32 v81, v81, v33
	v_sub_f32_e32 v80, v80, v33
	v_sub_f32_e32 v79, v79, v33
	v_sub_f32_e32 v78, v78, v33
	v_sub_f32_e32 v77, v77, v33
	v_sub_f32_e32 v76, v76, v33
	v_sub_f32_e32 v75, v75, v33
	v_sub_f32_e32 v74, v74, v33
	v_sub_f32_e32 v73, v73, v33
	v_sub_f32_e32 v72, v72, v33
	v_sub_f32_e32 v71, v71, v33
	v_sub_f32_e32 v70, v70, v33
	v_sub_f32_e32 v69, v69, v33
	v_sub_f32_e32 v68, v68, v33
	v_sub_f32_e32 v67, v67, v33
	v_sub_f32_e32 v66, v66, v33
	v_sub_f32_e32 v65, v65, v33
	v_sub_f32_e32 v64, v64, v33
	v_pk_mul_f32 v[14:15], v[14:15], v[34:35] op_sel_hi:[1,0]
	v_pk_mul_f32 v[12:13], v[12:13], v[34:35] op_sel_hi:[1,0]
	v_pk_mul_f32 v[10:11], v[10:11], v[34:35] op_sel_hi:[1,0]
	v_pk_mul_f32 v[8:9], v[8:9], v[34:35] op_sel_hi:[1,0]
	v_pk_mul_f32 v[6:7], v[6:7], v[34:35] op_sel_hi:[1,0]
	v_pk_mul_f32 v[4:5], v[4:5], v[34:35] op_sel_hi:[1,0]
	v_pk_mul_f32 v[2:3], v[2:3], v[34:35] op_sel_hi:[1,0]
	v_pk_mul_f32 v[0:1], v[0:1], v[34:35] op_sel_hi:[1,0]
	v_pk_mul_f32 v[30:31], v[30:31], v[34:35] op_sel_hi:[1,0]
	v_pk_mul_f32 v[28:29], v[28:29], v[34:35] op_sel_hi:[1,0]
	v_pk_mul_f32 v[26:27], v[26:27], v[34:35] op_sel_hi:[1,0]
	v_pk_mul_f32 v[24:25], v[24:25], v[34:35] op_sel_hi:[1,0]
	v_pk_mul_f32 v[22:23], v[22:23], v[34:35] op_sel_hi:[1,0]
	v_pk_mul_f32 v[20:21], v[20:21], v[34:35] op_sel_hi:[1,0]
	v_pk_mul_f32 v[18:19], v[18:19], v[34:35] op_sel_hi:[1,0]
	v_pk_mul_f32 v[16:17], v[16:17], v[34:35] op_sel_hi:[1,0]
	v_pk_mul_f32 v[184:185], v[184:185], v[34:35] op_sel_hi:[1,0]
	v_pk_mul_f32 v[186:187], v[186:187], v[34:35] op_sel_hi:[1,0]
	v_mov_b32_e32 v33, v32
	v_mov_b32_e32 v34, v32
	v_mov_b32_e32 v35, v32
	v_mov_b32_e32 v36, v32
	v_mov_b32_e32 v37, v32
	v_mov_b32_e32 v38, v32
	v_mov_b32_e32 v39, v32
	v_mov_b32_e32 v40, v32
	v_mov_b32_e32 v41, v32
	v_mov_b32_e32 v42, v32
	v_mov_b32_e32 v43, v32
	v_mov_b32_e32 v44, v32
	v_mov_b32_e32 v45, v32
	v_mov_b32_e32 v46, v32
	v_mov_b32_e32 v47, v32
	v_mov_b32_e32 v48, v32
	v_mov_b32_e32 v49, v32
	v_mov_b32_e32 v50, v32
	v_mov_b32_e32 v51, v32
	v_mov_b32_e32 v52, v32
	v_mov_b32_e32 v53, v32
	v_mov_b32_e32 v54, v32
	v_mov_b32_e32 v55, v32
	v_mov_b32_e32 v56, v32
	v_mov_b32_e32 v57, v32
	v_mov_b32_e32 v58, v32
	v_mov_b32_e32 v59, v32
	v_mov_b32_e32 v60, v32
	v_mov_b32_e32 v61, v32
	v_mov_b32_e32 v62, v32
	v_mov_b32_e32 v63, v32
	s_branch .LBB0_554
.LBB0_588:
	v_mov_b64_e32 v[32:33], v[48:49]
	v_mov_b64_e32 v[34:35], v[50:51]
	v_mov_b64_e32 v[36:37], v[52:53]
	v_mov_b64_e32 v[38:39], v[54:55]
	v_mov_b64_e32 v[40:41], v[56:57]
	v_mov_b64_e32 v[42:43], v[58:59]
	v_mov_b64_e32 v[44:45], v[60:61]
	v_mov_b64_e32 v[46:47], v[62:63]
	s_mov_b64 s[4:5], 0xff0000
	s_mov_b32 m0, s9
	v_lshl_add_u64 v[48:49], v[154:155], 0, s[4:5]
	s_mov_b64 s[4:5], 0x7f80
	global_load_lds_dwordx4 v[48:49], off
	v_lshl_add_u64 v[48:49], v[156:157], 0, s[4:5]
	s_mov_b32 m0, s7
	s_and_b64 vcc, exec, s[46:47]
	global_load_lds_dwordx4 v[48:49], off
	s_cbranch_vccz .LBB0_590
	s_mov_b64 s[4:5], 0xef10000
	v_lshl_add_u64 v[48:49], v[158:159], 0, s[4:5]
	s_mov_b32 m0, s6
	s_nop 0
	global_load_lds_dwordx4 v[48:49], off
